# swiglu mainloop half-specialized: waves 4-7 drop pre-MFMA barriers, waves 0-3 drop post-MFMA barriers (one barrier per phase), align/offset barriers removed
# speedup vs baseline: 1.0211x; 1.0044x over previous
.LBB7_346:
	s_and_b64 s[0:1], s[44:45], exec
	s_cselect_b32 s0, 0, 12
	v_readlane_b32 s1, v253, 53
	s_add_i32 s92, s1, s0
	s_cmp_le_i32 s87, s92
	s_cselect_b64 s[48:49], -1, 0
	s_cmp_lt_i32 s92, s89
	s_cselect_b64 s[0:1], -1, 0
	s_and_b64 s[0:1], s[48:49], s[0:1]
	s_andn2_b64 vcc, exec, s[0:1]
	s_cbranch_vccnz .LBB7_365
	v_readlane_b32 s4, v251, 16
	v_mov_b32_e32 v8, v200
	v_readlane_b32 s5, v251, 17
	s_mov_b32 s23, 16
	v_readfirstlane_b32 s0, v8
	s_andn2_b64 vcc, exec, s[4:5]
	s_cbranch_vccnz .LBB7_365
	v_lshlrev_b32_e32 v0, 4, v8
	s_waitcnt lgkmcnt(0)
	v_add_u32_e32 v2, 0x2000, v0
	v_ashrrev_i32_e32 v3, 31, v2
	v_lshrrev_b32_e32 v3, 22, v3
	v_add_u32_e32 v3, v2, v3
	v_ashrrev_i32_e32 v6, 10, v3
	v_mul_i32_i24_e32 v3, 0x400, v6
	v_sub_u32_e32 v2, v2, v3
	v_lshrrev_b32_e32 v3, 4, v2
	v_bitop3_b32 v2, v3, v2, 32 bitop3:0x6c
	s_ashr_i32 s3, s0, 6
	v_ashrrev_i32_e32 v3, 31, v2
	s_ashr_i32 s1, s0, 8
	s_lshl_b32 s84, s3, 10
	v_lshrrev_b32_e32 v3, 26, v3
	s_and_b64 s[4:5], s[44:45], exec
	v_add_u32_e32 v3, v2, v3
	v_lshlrev_b32_e32 v4, 3, v6
	s_cselect_b32 s4, 0, 0x1080000
	v_readlane_b32 s5, v254, 20
	v_ashrrev_i32_e32 v7, 6, v3
	v_and_b32_e32 v4, -16, v4
	s_add_u32 s85, s5, s4
	v_readlane_b32 s4, v254, 21
	v_add_u32_e32 v4, v7, v4
	s_addc_u32 s31, s4, 0
	v_and_b32_e32 v5, 3, v7
	s_mov_b32 s4, 0x1fffe0
	v_lshrrev_b32_e32 v9, 2, v4
	v_lshlrev_b32_e32 v10, 1, v4
	v_and_b32_e32 v3, 0xc0, v3
	v_and_or_b32 v5, v4, s4, v5
	v_and_b32_e32 v9, 4, v9
	v_and_b32_e32 v10, 24, v10
	v_sub_u32_e32 v2, v2, v3
	v_or3_b32 v5, v5, v9, v10
	v_lshlrev_b32_e32 v9, 5, v6
	v_ashrrev_i16_sdwa v2, v202, sext(v2) dst_sel:DWORD dst_unused:UNUSED_PAD src0_sel:DWORD src1_sel:BYTE_0
	v_and_b32_e32 v10, 32, v9
	v_bfe_i32 v9, v2, 0, 16
	v_add_lshl_u32 v2, v10, v9, 1
	s_waitcnt vmcnt(0)
	v_lshl_add_u32 v134, v5, 11, v2
	v_lshl_add_u32 v136, v4, 11, v2
	v_bfe_i32 v2, v8, 27, 1
	v_lshrrev_b32_e32 v2, 22, v2
	v_add_u32_e32 v2, v0, v2
	v_and_b32_e32 v2, 0xfffffc00, v2
	v_sub_u32_e32 v0, v0, v2
	v_lshrrev_b32_e32 v2, 4, v0
	v_ashrrev_i32_e32 v3, 31, v8
	v_bitop3_b32 v0, v2, v0, 32 bitop3:0x6c
	v_lshrrev_b32_e32 v3, 26, v3
	v_ashrrev_i32_e32 v2, 31, v0
	v_add_u32_e32 v3, v8, v3
	v_lshrrev_b32_e32 v2, 26, v2
	v_ashrrev_i32_e32 v11, 6, v3
	v_add_u32_e32 v2, v0, v2
	v_lshlrev_b32_e32 v3, 3, v11
	v_ashrrev_i32_e32 v10, 6, v2
	v_and_b32_e32 v3, -16, v3
	v_add_u32_e32 v3, v10, v3
	v_and_b32_e32 v4, 3, v10
	v_lshrrev_b32_e32 v5, 2, v3
	v_lshlrev_b32_e32 v12, 1, v3
	v_and_b32_e32 v2, 0xc0, v2
	v_and_or_b32 v4, v3, s4, v4
	v_and_b32_e32 v5, 4, v5
	v_and_b32_e32 v12, 24, v12
	v_sub_u32_e32 v0, v0, v2
	v_or3_b32 v4, v4, v5, v12
	v_lshlrev_b32_e32 v5, 5, v11
	v_ashrrev_i16_sdwa v0, v202, sext(v0) dst_sel:DWORD dst_unused:UNUSED_PAD src0_sel:DWORD src1_sel:BYTE_0
	v_readlane_b32 s4, v252, 14
	v_and_b32_e32 v5, 32, v5
	v_bfe_i32 v12, v0, 0, 16
	v_readlane_b32 s5, v252, 15
	s_add_u32 s42, s85, s4
	v_add_lshl_u32 v0, v5, v12, 1
	s_addc_u32 s43, s31, s5
	s_add_i32 s4, s84, 0
	v_lshl_add_u32 v138, v4, 11, v0
	s_add_i32 m0, s4, 0x10000
	v_lshl_add_u32 v140, v3, 11, v0
	global_load_lds_dwordx4 v138, s[42:43]
	s_add_i32 m0, s4, 0x12000
	s_add_u32 s6, s42, 0x40000
	global_load_lds_dwordx4 v134, s[42:43]
	s_addc_u32 s7, s43, 0
	s_add_i32 m0, s4, 0x14000
	s_add_i32 s5, s4, 0x2000
	global_load_lds_dwordx4 v138, s[6:7]
	s_add_i32 m0, s4, 0x16000
	s_add_i32 s93, s4, 0x4000
	global_load_lds_dwordx4 v134, s[6:7]
	v_readlane_b32 s6, v252, 18
	s_mov_b32 m0, s4
	v_readlane_b32 s7, v252, 19
	s_add_i32 s33, s4, 0x6000
	v_mov_b32_e32 v139, v1
	v_mov_b32_e32 v135, v1
	s_cmp_eq_u32 s1, 1
	v_lshl_add_u64 v[2:3], s[42:43], 0, v[138:139]
	global_load_lds_dwordx4 v140, s[6:7]
	s_mov_b32 m0, s5
	s_cselect_b64 s[50:51], -1, 0
	global_load_lds_dwordx4 v136, s[6:7]
	v_readlane_b32 s6, v252, 20
	s_mov_b32 m0, s93
	v_readlane_b32 s7, v252, 21
	s_cmp_lg_u32 s1, 1
	v_lshl_add_u64 v[4:5], s[42:43], 0, v[134:135]
	s_nop 2
	global_load_lds_dwordx4 v140, s[6:7]
	s_mov_b32 m0, s33
	s_nop 0
	global_load_lds_dwordx4 v136, s[6:7]
	s_cbranch_scc1 .LBB7_350
.LBB7_350:
	v_readlane_b32 s16, v252, 18
	s_lshl_b32 s9, s3, 5
	v_mov_b32_e32 v141, v1
	v_readlane_b32 s17, v252, 19
	s_and_b32 s96, s9, 0x60
	s_add_i32 m0, s4, 0x18000
	v_lshl_add_u64 v[2:3], v[2:3], 0, s[24:25]
	s_waitcnt vmcnt(0)
	v_lshl_add_u64 v[14:15], s[16:17], 0, v[140:141]
	v_mov_b32_e32 v137, v1
	s_lshl_b32 s8, s1, 13
	s_lshl_b32 s10, s96, 7
	s_waitcnt vmcnt(2)
	s_barrier
	global_load_lds_dwordx4 v[2:3], off
	v_lshl_add_u64 v[2:3], v[4:5], 0, s[24:25]
	s_add_i32 m0, s4, 0x1a000
	s_add_i32 s97, s4, 0x8000
	s_add_i32 s3, s4, 0xa000
	v_lshl_add_u64 v[16:17], s[16:17], 0, v[136:137]
	global_load_lds_dwordx4 v[2:3], off
	v_lshl_add_u64 v[2:3], v[14:15], 0, s[24:25]
	s_mov_b32 m0, s97
	s_add_u32 s6, s42, 0x40080
	global_load_lds_dwordx4 v[2:3], off
	v_lshl_add_u64 v[2:3], v[16:17], 0, s[24:25]
	s_mov_b32 m0, s3
	s_addc_u32 s7, s43, 0
	global_load_lds_dwordx4 v[2:3], off
	s_add_i32 m0, s4, 0x1c000
	v_lshl_add_u64 v[2:3], s[6:7], 0, v[138:139]
	global_load_lds_dwordx4 v[2:3], off
	v_lshl_add_u64 v[2:3], s[6:7], 0, v[134:135]
	s_add_i32 m0, s4, 0x1e000
	v_bfe_u32 v0, v8, 4, 2
	global_load_lds_dwordx4 v[2:3], off
	v_and_b32_e32 v2, 15, v8
	v_lshlrev_b32_e32 v3, 3, v0
	v_lshlrev_b32_e32 v0, 4, v0
	v_lshlrev_b32_e32 v4, 2, v8
	v_lshl_or_b32 v142, s1, 6, v2
	v_lshl_or_b32 v2, v2, 6, v0
	v_and_b32_e32 v4, 32, v4
	v_bitop3_b32 v5, v2, s8, v4 bitop3:0xde
	v_bitop3_b32 v179, v2, s10, v4 bitop3:0xde
	v_or_b32_e32 v2, 16, v142
	v_lshl_add_u64 v[144:145], s[66:67], 0, v[0:1]
	v_and_or_b32 v0, s9, 32, v3
	v_ashrrev_i32_e32 v3, 31, v2
	v_lshlrev_b64 v[148:149], 7, v[2:3]
	v_or_b32_e32 v2, 32, v142
	v_ashrrev_i32_e32 v3, 31, v2
	v_lshlrev_b64 v[150:151], 7, v[2:3]
	v_or_b32_e32 v2, 48, v142
	v_ashrrev_i32_e32 v3, 31, v2
	v_lshlrev_b64 v[152:153], 7, v[2:3]
	v_lshlrev_b32_e32 v2, 14, v11
	v_and_b32_e32 v2, 0xffff8000, v2
	v_ashrrev_i32_e32 v143, 31, v142
	v_lshl_add_u32 v2, v10, 11, v2
	v_and_b32_e32 v3, 1, v11
	s_cmpk_lt_u32 s0, 0x100
	v_lshlrev_b64 v[146:147], 7, v[142:143]
	s_mov_b64 s[0:1], 0x4000
	v_lshl_or_b32 v2, v3, 6, v2
	v_lshl_add_u64 v[154:155], v[146:147], 0, s[0:1]
	s_mov_b64 s[0:1], 0x4800
	v_lshl_add_u32 v174, v12, 1, v2
	v_lshlrev_b32_e32 v2, 14, v6
	v_lshl_add_u64 v[156:157], v[146:147], 0, s[0:1]
	s_mov_b64 s[0:1], 0x5000
	v_and_b32_e32 v2, 0xffff8000, v2
	s_waitcnt vmcnt(6)
	v_lshl_add_u64 v[158:159], v[146:147], 0, s[0:1]
	s_mov_b64 s[0:1], 0x5800
	v_lshl_add_u32 v2, v7, 11, v2
	v_and_b32_e32 v3, 1, v6
	s_cselect_b64 s[52:53], -1, 0
	v_lshl_add_u64 v[160:161], v[146:147], 0, s[0:1]
	s_cmp_gt_i32 s23, 0
	v_lshl_or_b32 v2, v3, 6, v2
	v_readlane_b32 s0, v252, 16
	s_mov_b32 s22, 0
	s_cselect_b64 s[54:55], -1, 0
	s_add_i32 s20, s23, -2
	v_mov_b32_e32 v175, v1
	v_lshl_add_u32 v176, v9, 1, v2
	v_mov_b32_e32 v177, v1
	v_add_u32_e32 v143, 0, v5
	v_lshlrev_b32_e32 v0, 1, v0
	v_readlane_b32 s10, v252, 13
	s_mov_b32 s38, s0
	s_movk_i32 s76, 0x161
	s_barrier
	v_readlane_b32 s1, v252, 17
	s_branch .LBB7_353

.LBB7_355:
	s_add_u32 s0, s68, s14
	s_addc_u32 s1, s69, s15
	s_add_u32 s6, s85, s18
	s_addc_u32 s7, s31, s19
	s_andn2_b64 vcc, exec, s[54:55]
	s_cbranch_vccnz .LBB7_363
	s_and_b64 s[28:29], s[40:41], exec
	s_cselect_b32 s9, s1, s17
	s_cselect_b32 s13, s0, s16
	s_cselect_b32 s28, s7, s43
	s_cselect_b32 s39, s6, s42
	s_add_u32 s16, s16, 0x40080
	s_addc_u32 s17, s17, 0
	s_add_u32 s56, s42, 0x100
	v_mov_b32_e32 v2, 0
	s_addc_u32 s57, s43, 0
	s_mov_b32 s42, 0
	v_mov_b32_e32 v3, v2
	v_mov_b32_e32 v4, v2
	v_mov_b32_e32 v5, v2
	v_mov_b32_e32 v10, v2
	v_mov_b32_e32 v11, v2
	v_mov_b32_e32 v12, v2
	v_mov_b32_e32 v13, v2
	v_mov_b32_e32 v18, v2
	v_mov_b32_e32 v19, v2
	v_mov_b32_e32 v20, v2
	v_mov_b32_e32 v21, v2
	v_mov_b32_e32 v26, v2
	v_mov_b32_e32 v27, v2
	v_mov_b32_e32 v28, v2
	v_mov_b32_e32 v29, v2
	v_mov_b32_e32 v34, v2
	v_mov_b32_e32 v35, v2
	v_mov_b32_e32 v36, v2
	v_mov_b32_e32 v37, v2
	v_mov_b32_e32 v42, v2
	v_mov_b32_e32 v43, v2
	v_mov_b32_e32 v44, v2
	v_mov_b32_e32 v45, v2
	v_mov_b32_e32 v50, v2
	v_mov_b32_e32 v51, v2
	v_mov_b32_e32 v52, v2
	v_mov_b32_e32 v53, v2
	v_mov_b32_e32 v58, v2
	v_mov_b32_e32 v59, v2
	v_mov_b32_e32 v60, v2
	v_mov_b32_e32 v61, v2
	v_mov_b32_e32 v6, v2
	v_mov_b32_e32 v7, v2
	v_mov_b32_e32 v8, v2
	v_mov_b32_e32 v9, v2
	v_mov_b32_e32 v14, v2
	v_mov_b32_e32 v15, v2
	v_mov_b32_e32 v16, v2
	v_mov_b32_e32 v17, v2
	v_mov_b32_e32 v22, v2
	v_mov_b32_e32 v23, v2
	v_mov_b32_e32 v24, v2
	v_mov_b32_e32 v25, v2
	v_mov_b32_e32 v30, v2
	v_mov_b32_e32 v31, v2
	v_mov_b32_e32 v32, v2
	v_mov_b32_e32 v33, v2
	v_mov_b32_e32 v38, v2
	v_mov_b32_e32 v39, v2
	v_mov_b32_e32 v40, v2
	v_mov_b32_e32 v41, v2
	v_mov_b32_e32 v46, v2
	v_mov_b32_e32 v47, v2
	v_mov_b32_e32 v48, v2
	v_mov_b32_e32 v49, v2
	v_mov_b32_e32 v54, v2
	v_mov_b32_e32 v55, v2
	v_mov_b32_e32 v56, v2
	v_mov_b32_e32 v57, v2
	v_mov_b32_e32 v62, v2
	v_mov_b32_e32 v63, v2
	v_mov_b32_e32 v64, v2
	v_mov_b32_e32 v65, v2
	v_mov_b32_e32 v66, v2
	v_mov_b32_e32 v67, v2
	v_mov_b32_e32 v68, v2
	v_mov_b32_e32 v69, v2
	v_mov_b32_e32 v74, v2
	v_mov_b32_e32 v75, v2
	v_mov_b32_e32 v76, v2
	v_mov_b32_e32 v77, v2
	v_mov_b32_e32 v82, v2
	v_mov_b32_e32 v83, v2
	v_mov_b32_e32 v84, v2
	v_mov_b32_e32 v85, v2
	v_mov_b32_e32 v90, v2
	v_mov_b32_e32 v91, v2
	v_mov_b32_e32 v92, v2
	v_mov_b32_e32 v93, v2
	v_mov_b32_e32 v98, v2
	v_mov_b32_e32 v99, v2
	v_mov_b32_e32 v100, v2
	v_mov_b32_e32 v101, v2
	v_mov_b32_e32 v106, v2
	v_mov_b32_e32 v107, v2
	v_mov_b32_e32 v108, v2
	v_mov_b32_e32 v109, v2
	v_mov_b32_e32 v114, v2
	v_mov_b32_e32 v115, v2
	v_mov_b32_e32 v116, v2
	v_mov_b32_e32 v117, v2
	v_mov_b32_e32 v122, v2
	v_mov_b32_e32 v123, v2
	v_mov_b32_e32 v124, v2
	v_mov_b32_e32 v125, v2
	v_mov_b32_e32 v70, v2
	v_mov_b32_e32 v71, v2
	v_mov_b32_e32 v72, v2
	v_mov_b32_e32 v73, v2
	v_mov_b32_e32 v78, v2
	v_mov_b32_e32 v79, v2
	v_mov_b32_e32 v80, v2
	v_mov_b32_e32 v81, v2
	v_mov_b32_e32 v86, v2
	v_mov_b32_e32 v87, v2
	v_mov_b32_e32 v88, v2
	v_mov_b32_e32 v89, v2
	v_mov_b32_e32 v94, v2
	v_mov_b32_e32 v95, v2
	v_mov_b32_e32 v96, v2
	v_mov_b32_e32 v97, v2
	v_mov_b32_e32 v102, v2
	v_mov_b32_e32 v103, v2
	v_mov_b32_e32 v104, v2
	v_mov_b32_e32 v105, v2
	v_mov_b32_e32 v110, v2
	v_mov_b32_e32 v111, v2
	v_mov_b32_e32 v112, v2
	v_mov_b32_e32 v113, v2
	v_mov_b32_e32 v118, v2
	v_mov_b32_e32 v119, v2
	v_mov_b32_e32 v120, v2
	v_mov_b32_e32 v121, v2
	v_mov_b32_e32 v126, v2
	v_mov_b32_e32 v127, v2
	v_mov_b32_e32 v128, v2
	v_mov_b32_e32 v129, v2
	s_and_b64 vcc, exec, s[50:51]
	s_cbranch_vccnz .Lswi_loopL
.LBB7_357:
	s_add_i32 s86, s42, 2
	s_add_u32 s29, s16, 0xfffc0080
	s_addc_u32 s37, s17, -1
	s_add_i32 s74, 0, 0x10000
	s_cmp_eq_u32 s20, s42
	s_cselect_b32 s73, s9, s37
	s_cselect_b32 s72, s13, s29
	v_add_u32_e32 v170, s74, v179
	s_cselect_b32 s43, s28, s57
	s_cselect_b32 s42, s39, s56
	s_add_i32 s29, 0, 0x14000
	ds_read_b128 v[130:133], v170
	ds_read_b128 v[180:183], v170 offset:1024
	ds_read_b128 v[184:187], v170 offset:2048
	ds_read_b128 v[188:191], v170 offset:3072
	v_add_u32_e32 v170, s29, v179
	ds_read_b128 v[192:195], v170
	ds_read_b128 v[196:199], v170 offset:1024
	ds_read_b128 v[204:207], v170 offset:2048
	ds_read_b128 v[208:211], v170 offset:3072
	s_add_i32 m0, s4, 0xc000
	ds_read_b128 v[212:215], v143
	ds_read_b128 v[216:219], v143 offset:1024
	ds_read_b128 v[220:223], v143 offset:2048
	ds_read_b128 v[224:227], v143 offset:3072
	ds_read_b128 v[228:231], v143 offset:4096
	ds_read_b128 v[232:235], v143 offset:5120
	ds_read_b128 v[236:239], v143 offset:6144
	ds_read_b128 v[240:243], v143 offset:7168
	global_load_lds_dwordx4 v174, s[16:17]
	s_add_i32 m0, s4, 0xe000
	s_nop 0
	global_load_lds_dwordx4 v176, s[16:17]
	s_waitcnt vmcnt(8)
	s_waitcnt lgkmcnt(0)
	s_setprio 1
	s_barrier
	v_mfma_f32_16x16x32_bf16 v[126:129], v[130:133], v[212:215], v[126:129]
	v_mfma_f32_16x16x32_bf16 v[118:121], v[184:187], v[212:215], v[118:121]
	v_mfma_f32_16x16x32_bf16 v[110:113], v[130:133], v[220:223], v[110:113]
	v_mfma_f32_16x16x32_bf16 v[102:105], v[184:187], v[220:223], v[102:105]
	v_mfma_f32_16x16x32_bf16 v[94:97], v[130:133], v[228:231], v[94:97]
	v_mfma_f32_16x16x32_bf16 v[86:89], v[184:187], v[228:231], v[86:89]
	v_mfma_f32_16x16x32_bf16 v[78:81], v[130:133], v[236:239], v[78:81]
	v_mfma_f32_16x16x32_bf16 v[70:73], v[184:187], v[236:239], v[70:73]
	v_mfma_f32_16x16x32_bf16 v[126:129], v[180:183], v[216:219], v[126:129]
	v_mfma_f32_16x16x32_bf16 v[118:121], v[188:191], v[216:219], v[118:121]
	v_mfma_f32_16x16x32_bf16 v[110:113], v[180:183], v[224:227], v[110:113]
	v_mfma_f32_16x16x32_bf16 v[102:105], v[188:191], v[224:227], v[102:105]
	v_mfma_f32_16x16x32_bf16 v[94:97], v[180:183], v[232:235], v[94:97]
	v_mfma_f32_16x16x32_bf16 v[86:89], v[188:191], v[232:235], v[86:89]
	v_mfma_f32_16x16x32_bf16 v[78:81], v[180:183], v[240:243], v[78:81]
	v_mfma_f32_16x16x32_bf16 v[70:73], v[188:191], v[240:243], v[70:73]
	v_mfma_f32_16x16x32_bf16 v[122:125], v[192:195], v[212:215], v[122:125]
	v_mfma_f32_16x16x32_bf16 v[114:117], v[204:207], v[212:215], v[114:117]
	v_mfma_f32_16x16x32_bf16 v[106:109], v[192:195], v[220:223], v[106:109]
	v_mfma_f32_16x16x32_bf16 v[98:101], v[204:207], v[220:223], v[98:101]
	v_mfma_f32_16x16x32_bf16 v[90:93], v[192:195], v[228:231], v[90:93]
	v_mfma_f32_16x16x32_bf16 v[82:85], v[204:207], v[228:231], v[82:85]
	v_mfma_f32_16x16x32_bf16 v[74:77], v[192:195], v[236:239], v[74:77]
	v_mfma_f32_16x16x32_bf16 v[66:69], v[204:207], v[236:239], v[66:69]
	v_mfma_f32_16x16x32_bf16 v[122:125], v[196:199], v[216:219], v[122:125]
	v_mfma_f32_16x16x32_bf16 v[114:117], v[208:211], v[216:219], v[114:117]
	v_mfma_f32_16x16x32_bf16 v[106:109], v[196:199], v[224:227], v[106:109]
	v_mfma_f32_16x16x32_bf16 v[98:101], v[208:211], v[224:227], v[98:101]
	v_mfma_f32_16x16x32_bf16 v[90:93], v[196:199], v[232:235], v[90:93]
	v_mfma_f32_16x16x32_bf16 v[82:85], v[208:211], v[232:235], v[82:85]
	v_mfma_f32_16x16x32_bf16 v[74:77], v[196:199], v[240:243], v[74:77]
	v_mfma_f32_16x16x32_bf16 v[66:69], v[208:211], v[240:243], v[66:69]
	s_setprio 0
	s_add_i32 s37, s74, s84
	v_lshl_add_u64 v[244:245], s[42:43], 0, v[138:139]
	s_mov_b32 m0, s37
	ds_read_b128 v[212:215], v143 offset:16384
	ds_read_b128 v[216:219], v143 offset:17408
	ds_read_b128 v[220:223], v143 offset:18432
	ds_read_b128 v[224:227], v143 offset:19456
	ds_read_b128 v[228:231], v143 offset:20480
	ds_read_b128 v[232:235], v143 offset:21504
	ds_read_b128 v[236:239], v143 offset:22528
	ds_read_b128 v[240:243], v143 offset:23552
	global_load_lds_dwordx4 v[244:245], off
	s_add_i32 m0, s37, 0x2000
	s_add_u32 s74, s42, 0x40000
	v_lshl_add_u64 v[246:247], s[42:43], 0, v[134:135]
	s_addc_u32 s75, s43, 0
	s_add_i32 s29, s29, s84
	global_load_lds_dwordx4 v[246:247], off
	s_mov_b32 m0, s29
	v_lshl_add_u64 v[170:171], s[72:73], 0, v[136:137]
	global_load_lds_dwordx4 v138, s[74:75]
	s_add_i32 m0, s29, 0x2000
	s_nop 0
	global_load_lds_dwordx4 v134, s[74:75]
	v_lshl_add_u64 v[248:249], s[72:73], 0, v[140:141]
	s_mov_b32 m0, s4
	s_nop 0
	global_load_lds_dwordx4 v[248:249], off
	s_mov_b32 m0, s5
	s_nop 0
	global_load_lds_dwordx4 v[170:171], off
	s_waitcnt vmcnt(8)
	s_waitcnt lgkmcnt(0)
	s_setprio 1
	s_barrier
	v_mfma_f32_16x16x32_bf16 v[62:65], v[130:133], v[212:215], v[62:65]
	v_mfma_f32_16x16x32_bf16 v[54:57], v[184:187], v[212:215], v[54:57]
	v_mfma_f32_16x16x32_bf16 v[46:49], v[130:133], v[220:223], v[46:49]
	v_mfma_f32_16x16x32_bf16 v[38:41], v[184:187], v[220:223], v[38:41]
	v_mfma_f32_16x16x32_bf16 v[30:33], v[130:133], v[228:231], v[30:33]
	v_mfma_f32_16x16x32_bf16 v[22:25], v[184:187], v[228:231], v[22:25]
	v_mfma_f32_16x16x32_bf16 v[14:17], v[130:133], v[236:239], v[14:17]
	v_mfma_f32_16x16x32_bf16 v[6:9], v[184:187], v[236:239], v[6:9]
	v_mfma_f32_16x16x32_bf16 v[62:65], v[180:183], v[216:219], v[62:65]
	v_mfma_f32_16x16x32_bf16 v[54:57], v[188:191], v[216:219], v[54:57]
	v_mfma_f32_16x16x32_bf16 v[46:49], v[180:183], v[224:227], v[46:49]
	v_mfma_f32_16x16x32_bf16 v[38:41], v[188:191], v[224:227], v[38:41]
	v_mfma_f32_16x16x32_bf16 v[30:33], v[180:183], v[232:235], v[30:33]
	v_mfma_f32_16x16x32_bf16 v[22:25], v[188:191], v[232:235], v[22:25]
	v_mfma_f32_16x16x32_bf16 v[14:17], v[180:183], v[240:243], v[14:17]
	v_mfma_f32_16x16x32_bf16 v[6:9], v[188:191], v[240:243], v[6:9]
	v_mfma_f32_16x16x32_bf16 v[58:61], v[192:195], v[212:215], v[58:61]
	v_mfma_f32_16x16x32_bf16 v[50:53], v[204:207], v[212:215], v[50:53]
	v_mfma_f32_16x16x32_bf16 v[42:45], v[192:195], v[220:223], v[42:45]
	v_mfma_f32_16x16x32_bf16 v[34:37], v[204:207], v[220:223], v[34:37]
	v_mfma_f32_16x16x32_bf16 v[26:29], v[192:195], v[228:231], v[26:29]
	v_mfma_f32_16x16x32_bf16 v[18:21], v[204:207], v[228:231], v[18:21]
	v_mfma_f32_16x16x32_bf16 v[10:13], v[192:195], v[236:239], v[10:13]
	v_mfma_f32_16x16x32_bf16 v[2:5], v[204:207], v[236:239], v[2:5]
	v_mfma_f32_16x16x32_bf16 v[58:61], v[196:199], v[216:219], v[58:61]
	v_mfma_f32_16x16x32_bf16 v[50:53], v[208:211], v[216:219], v[50:53]
	v_mfma_f32_16x16x32_bf16 v[42:45], v[196:199], v[224:227], v[42:45]
	v_mfma_f32_16x16x32_bf16 v[34:37], v[208:211], v[224:227], v[34:37]
	v_mfma_f32_16x16x32_bf16 v[26:29], v[196:199], v[232:235], v[26:29]
	v_mfma_f32_16x16x32_bf16 v[18:21], v[208:211], v[232:235], v[18:21]
	v_mfma_f32_16x16x32_bf16 v[10:13], v[196:199], v[240:243], v[10:13]
	v_mfma_f32_16x16x32_bf16 v[2:5], v[208:211], v[240:243], v[2:5]
	s_setprio 0
	s_add_i32 s29, 0, 0x18000
	v_add_u32_e32 v172, s29, v179
	s_add_i32 s37, 0, 0x1c000
	ds_read_b128 v[130:133], v172
	ds_read_b128 v[180:183], v172 offset:1024
	ds_read_b128 v[184:187], v172 offset:2048
	ds_read_b128 v[188:191], v172 offset:3072
	v_add_u32_e32 v172, s37, v179
	ds_read_b128 v[192:195], v172
	ds_read_b128 v[196:199], v172 offset:1024
	ds_read_b128 v[204:207], v172 offset:2048
	ds_read_b128 v[208:211], v172 offset:3072
	s_add_u32 s72, s72, 0x40000
	s_addc_u32 s73, s73, 0
	s_mov_b32 m0, s93
	ds_read_b128 v[212:215], v143 offset:32768
	ds_read_b128 v[216:219], v143 offset:33792
	ds_read_b128 v[220:223], v143 offset:34816
	ds_read_b128 v[224:227], v143 offset:35840
	ds_read_b128 v[228:231], v143 offset:36864
	ds_read_b128 v[232:235], v143 offset:37888
	ds_read_b128 v[236:239], v143 offset:38912
	ds_read_b128 v[240:243], v143 offset:39936
	global_load_lds_dwordx4 v140, s[72:73]
	s_mov_b32 m0, s33
	s_nop 0
	global_load_lds_dwordx4 v136, s[72:73]
	s_waitcnt vmcnt(8)
	s_waitcnt lgkmcnt(0)
	s_setprio 1
	s_barrier
	v_mfma_f32_16x16x32_bf16 v[126:129], v[130:133], v[212:215], v[126:129]
	v_mfma_f32_16x16x32_bf16 v[118:121], v[184:187], v[212:215], v[118:121]
	v_mfma_f32_16x16x32_bf16 v[110:113], v[130:133], v[220:223], v[110:113]
	v_mfma_f32_16x16x32_bf16 v[102:105], v[184:187], v[220:223], v[102:105]
	v_mfma_f32_16x16x32_bf16 v[94:97], v[130:133], v[228:231], v[94:97]
	v_mfma_f32_16x16x32_bf16 v[86:89], v[184:187], v[228:231], v[86:89]
	v_mfma_f32_16x16x32_bf16 v[78:81], v[130:133], v[236:239], v[78:81]
	v_mfma_f32_16x16x32_bf16 v[70:73], v[184:187], v[236:239], v[70:73]
	v_mfma_f32_16x16x32_bf16 v[126:129], v[180:183], v[216:219], v[126:129]
	v_mfma_f32_16x16x32_bf16 v[118:121], v[188:191], v[216:219], v[118:121]
	v_mfma_f32_16x16x32_bf16 v[110:113], v[180:183], v[224:227], v[110:113]
	v_mfma_f32_16x16x32_bf16 v[102:105], v[188:191], v[224:227], v[102:105]
	v_mfma_f32_16x16x32_bf16 v[94:97], v[180:183], v[232:235], v[94:97]
	v_mfma_f32_16x16x32_bf16 v[86:89], v[188:191], v[232:235], v[86:89]
	v_mfma_f32_16x16x32_bf16 v[78:81], v[180:183], v[240:243], v[78:81]
	v_mfma_f32_16x16x32_bf16 v[70:73], v[188:191], v[240:243], v[70:73]
	v_mfma_f32_16x16x32_bf16 v[122:125], v[192:195], v[212:215], v[122:125]
	v_mfma_f32_16x16x32_bf16 v[114:117], v[204:207], v[212:215], v[114:117]
	v_mfma_f32_16x16x32_bf16 v[106:109], v[192:195], v[220:223], v[106:109]
	v_mfma_f32_16x16x32_bf16 v[98:101], v[204:207], v[220:223], v[98:101]
	v_mfma_f32_16x16x32_bf16 v[90:93], v[192:195], v[228:231], v[90:93]
	v_mfma_f32_16x16x32_bf16 v[82:85], v[204:207], v[228:231], v[82:85]
	v_mfma_f32_16x16x32_bf16 v[74:77], v[192:195], v[236:239], v[74:77]
	v_mfma_f32_16x16x32_bf16 v[66:69], v[204:207], v[236:239], v[66:69]
	v_mfma_f32_16x16x32_bf16 v[122:125], v[196:199], v[216:219], v[122:125]
	v_mfma_f32_16x16x32_bf16 v[114:117], v[208:211], v[216:219], v[114:117]
	v_mfma_f32_16x16x32_bf16 v[106:109], v[196:199], v[224:227], v[106:109]
	v_mfma_f32_16x16x32_bf16 v[98:101], v[208:211], v[224:227], v[98:101]
	v_mfma_f32_16x16x32_bf16 v[90:93], v[196:199], v[232:235], v[90:93]
	v_mfma_f32_16x16x32_bf16 v[82:85], v[208:211], v[232:235], v[82:85]
	v_mfma_f32_16x16x32_bf16 v[74:77], v[196:199], v[240:243], v[74:77]
	v_mfma_f32_16x16x32_bf16 v[66:69], v[208:211], v[240:243], v[66:69]
	s_setprio 0
	s_add_i32 s29, s29, s84
	v_lshl_add_u64 v[172:173], v[244:245], 0, s[24:25]
	s_mov_b32 m0, s29
	ds_read_b128 v[212:215], v143 offset:49152
	ds_read_b128 v[216:219], v143 offset:50176
	ds_read_b128 v[220:223], v143 offset:51200
	ds_read_b128 v[224:227], v143 offset:52224
	ds_read_b128 v[228:231], v143 offset:53248
	ds_read_b128 v[232:235], v143 offset:54272
	ds_read_b128 v[236:239], v143 offset:55296
	ds_read_b128 v[240:243], v143 offset:56320
	global_load_lds_dwordx4 v[172:173], off
	s_add_i32 m0, s29, 0x2000
	s_add_u32 s42, s42, 0x40080
	v_lshl_add_u64 v[172:173], v[246:247], 0, s[24:25]
	s_addc_u32 s43, s43, 0
	s_add_i32 s29, s37, s84
	global_load_lds_dwordx4 v[172:173], off
	s_mov_b32 m0, s29
	v_lshl_add_u64 v[170:171], v[170:171], 0, s[24:25]
	global_load_lds_dwordx4 v138, s[42:43]
	s_add_i32 m0, s29, 0x2000
	s_nop 0
	global_load_lds_dwordx4 v134, s[42:43]
	v_lshl_add_u64 v[172:173], v[248:249], 0, s[24:25]
	s_mov_b32 m0, s97
	s_nop 0
	global_load_lds_dwordx4 v[172:173], off
	s_mov_b32 m0, s3
	s_nop 0
	global_load_lds_dwordx4 v[170:171], off
	s_waitcnt vmcnt(8)
	s_waitcnt lgkmcnt(0)
	s_setprio 1
	s_barrier
	v_mfma_f32_16x16x32_bf16 v[62:65], v[130:133], v[212:215], v[62:65]
	v_mfma_f32_16x16x32_bf16 v[54:57], v[184:187], v[212:215], v[54:57]
	v_mfma_f32_16x16x32_bf16 v[46:49], v[130:133], v[220:223], v[46:49]
	v_mfma_f32_16x16x32_bf16 v[38:41], v[184:187], v[220:223], v[38:41]
	v_mfma_f32_16x16x32_bf16 v[30:33], v[130:133], v[228:231], v[30:33]
	v_mfma_f32_16x16x32_bf16 v[22:25], v[184:187], v[228:231], v[22:25]
	v_mfma_f32_16x16x32_bf16 v[14:17], v[130:133], v[236:239], v[14:17]
	v_mfma_f32_16x16x32_bf16 v[6:9], v[184:187], v[236:239], v[6:9]
	v_mfma_f32_16x16x32_bf16 v[62:65], v[180:183], v[216:219], v[62:65]
	v_mfma_f32_16x16x32_bf16 v[54:57], v[188:191], v[216:219], v[54:57]
	v_mfma_f32_16x16x32_bf16 v[46:49], v[180:183], v[224:227], v[46:49]
	v_mfma_f32_16x16x32_bf16 v[38:41], v[188:191], v[224:227], v[38:41]
	v_mfma_f32_16x16x32_bf16 v[30:33], v[180:183], v[232:235], v[30:33]
	v_mfma_f32_16x16x32_bf16 v[22:25], v[188:191], v[232:235], v[22:25]
	v_mfma_f32_16x16x32_bf16 v[14:17], v[180:183], v[240:243], v[14:17]
	v_mfma_f32_16x16x32_bf16 v[6:9], v[188:191], v[240:243], v[6:9]
	v_mfma_f32_16x16x32_bf16 v[58:61], v[192:195], v[212:215], v[58:61]
	v_mfma_f32_16x16x32_bf16 v[50:53], v[204:207], v[212:215], v[50:53]
	v_mfma_f32_16x16x32_bf16 v[42:45], v[192:195], v[220:223], v[42:45]
	v_mfma_f32_16x16x32_bf16 v[34:37], v[204:207], v[220:223], v[34:37]
	v_mfma_f32_16x16x32_bf16 v[26:29], v[192:195], v[228:231], v[26:29]
	v_mfma_f32_16x16x32_bf16 v[18:21], v[204:207], v[228:231], v[18:21]
	v_mfma_f32_16x16x32_bf16 v[10:13], v[192:195], v[236:239], v[10:13]
	v_mfma_f32_16x16x32_bf16 v[2:5], v[204:207], v[236:239], v[2:5]
	v_mfma_f32_16x16x32_bf16 v[58:61], v[196:199], v[216:219], v[58:61]
	v_mfma_f32_16x16x32_bf16 v[50:53], v[208:211], v[216:219], v[50:53]
	v_mfma_f32_16x16x32_bf16 v[42:45], v[196:199], v[224:227], v[42:45]
	v_mfma_f32_16x16x32_bf16 v[34:37], v[208:211], v[224:227], v[34:37]
	v_mfma_f32_16x16x32_bf16 v[26:29], v[196:199], v[232:235], v[26:29]
	v_mfma_f32_16x16x32_bf16 v[18:21], v[208:211], v[232:235], v[18:21]
	v_mfma_f32_16x16x32_bf16 v[10:13], v[196:199], v[240:243], v[10:13]
	v_mfma_f32_16x16x32_bf16 v[2:5], v[208:211], v[240:243], v[2:5]
	s_setprio 0
	s_add_u32 s16, s16, 0x100
	s_addc_u32 s17, s17, 0
	s_add_u32 s56, s56, 0x100
	s_addc_u32 s57, s57, 0
	s_cmp_ge_i32 s86, s23
	s_mov_b32 s42, s86
	s_cbranch_scc0 .LBB7_357
	s_branch .Lswi_exit
.Lswi_loopL:
	s_add_i32 s86, s42, 2
	s_add_u32 s29, s16, 0xfffc0080
	s_addc_u32 s37, s17, -1
	s_add_i32 s74, 0, 0x10000
	s_cmp_eq_u32 s20, s42
	s_cselect_b32 s73, s9, s37
	s_cselect_b32 s72, s13, s29
	v_add_u32_e32 v170, s74, v179
	s_cselect_b32 s43, s28, s57
	s_cselect_b32 s42, s39, s56
	s_add_i32 s29, 0, 0x14000
	ds_read_b128 v[130:133], v170
	ds_read_b128 v[180:183], v170 offset:1024
	ds_read_b128 v[184:187], v170 offset:2048
	ds_read_b128 v[188:191], v170 offset:3072
	v_add_u32_e32 v170, s29, v179
	ds_read_b128 v[192:195], v170
	ds_read_b128 v[196:199], v170 offset:1024
	ds_read_b128 v[204:207], v170 offset:2048
	ds_read_b128 v[208:211], v170 offset:3072
	s_add_i32 m0, s4, 0xc000
	ds_read_b128 v[212:215], v143
	ds_read_b128 v[216:219], v143 offset:1024
	ds_read_b128 v[220:223], v143 offset:2048
	ds_read_b128 v[224:227], v143 offset:3072
	ds_read_b128 v[228:231], v143 offset:4096
	ds_read_b128 v[232:235], v143 offset:5120
	ds_read_b128 v[236:239], v143 offset:6144
	ds_read_b128 v[240:243], v143 offset:7168
	global_load_lds_dwordx4 v174, s[16:17]
	s_add_i32 m0, s4, 0xe000
	s_nop 0
	global_load_lds_dwordx4 v176, s[16:17]
	s_waitcnt vmcnt(8)
	s_waitcnt lgkmcnt(0)
	s_setprio 1
	v_mfma_f32_16x16x32_bf16 v[126:129], v[130:133], v[212:215], v[126:129]
	v_mfma_f32_16x16x32_bf16 v[118:121], v[184:187], v[212:215], v[118:121]
	v_mfma_f32_16x16x32_bf16 v[110:113], v[130:133], v[220:223], v[110:113]
	v_mfma_f32_16x16x32_bf16 v[102:105], v[184:187], v[220:223], v[102:105]
	v_mfma_f32_16x16x32_bf16 v[94:97], v[130:133], v[228:231], v[94:97]
	v_mfma_f32_16x16x32_bf16 v[86:89], v[184:187], v[228:231], v[86:89]
	v_mfma_f32_16x16x32_bf16 v[78:81], v[130:133], v[236:239], v[78:81]
	v_mfma_f32_16x16x32_bf16 v[70:73], v[184:187], v[236:239], v[70:73]
	v_mfma_f32_16x16x32_bf16 v[126:129], v[180:183], v[216:219], v[126:129]
	v_mfma_f32_16x16x32_bf16 v[118:121], v[188:191], v[216:219], v[118:121]
	v_mfma_f32_16x16x32_bf16 v[110:113], v[180:183], v[224:227], v[110:113]
	v_mfma_f32_16x16x32_bf16 v[102:105], v[188:191], v[224:227], v[102:105]
	v_mfma_f32_16x16x32_bf16 v[94:97], v[180:183], v[232:235], v[94:97]
	v_mfma_f32_16x16x32_bf16 v[86:89], v[188:191], v[232:235], v[86:89]
	v_mfma_f32_16x16x32_bf16 v[78:81], v[180:183], v[240:243], v[78:81]
	v_mfma_f32_16x16x32_bf16 v[70:73], v[188:191], v[240:243], v[70:73]
	v_mfma_f32_16x16x32_bf16 v[122:125], v[192:195], v[212:215], v[122:125]
	v_mfma_f32_16x16x32_bf16 v[114:117], v[204:207], v[212:215], v[114:117]
	v_mfma_f32_16x16x32_bf16 v[106:109], v[192:195], v[220:223], v[106:109]
	v_mfma_f32_16x16x32_bf16 v[98:101], v[204:207], v[220:223], v[98:101]
	v_mfma_f32_16x16x32_bf16 v[90:93], v[192:195], v[228:231], v[90:93]
	v_mfma_f32_16x16x32_bf16 v[82:85], v[204:207], v[228:231], v[82:85]
	v_mfma_f32_16x16x32_bf16 v[74:77], v[192:195], v[236:239], v[74:77]
	v_mfma_f32_16x16x32_bf16 v[66:69], v[204:207], v[236:239], v[66:69]
	v_mfma_f32_16x16x32_bf16 v[122:125], v[196:199], v[216:219], v[122:125]
	v_mfma_f32_16x16x32_bf16 v[114:117], v[208:211], v[216:219], v[114:117]
	v_mfma_f32_16x16x32_bf16 v[106:109], v[196:199], v[224:227], v[106:109]
	v_mfma_f32_16x16x32_bf16 v[98:101], v[208:211], v[224:227], v[98:101]
	v_mfma_f32_16x16x32_bf16 v[90:93], v[196:199], v[232:235], v[90:93]
	v_mfma_f32_16x16x32_bf16 v[82:85], v[208:211], v[232:235], v[82:85]
	v_mfma_f32_16x16x32_bf16 v[74:77], v[196:199], v[240:243], v[74:77]
	v_mfma_f32_16x16x32_bf16 v[66:69], v[208:211], v[240:243], v[66:69]
	s_barrier
	s_setprio 0
	s_add_i32 s37, s74, s84
	v_lshl_add_u64 v[244:245], s[42:43], 0, v[138:139]
	s_mov_b32 m0, s37
	ds_read_b128 v[212:215], v143 offset:16384
	ds_read_b128 v[216:219], v143 offset:17408
	ds_read_b128 v[220:223], v143 offset:18432
	ds_read_b128 v[224:227], v143 offset:19456
	ds_read_b128 v[228:231], v143 offset:20480
	ds_read_b128 v[232:235], v143 offset:21504
	ds_read_b128 v[236:239], v143 offset:22528
	ds_read_b128 v[240:243], v143 offset:23552
	global_load_lds_dwordx4 v[244:245], off
	s_add_i32 m0, s37, 0x2000
	s_add_u32 s74, s42, 0x40000
	v_lshl_add_u64 v[246:247], s[42:43], 0, v[134:135]
	s_addc_u32 s75, s43, 0
	s_add_i32 s29, s29, s84
	global_load_lds_dwordx4 v[246:247], off
	s_mov_b32 m0, s29
	v_lshl_add_u64 v[170:171], s[72:73], 0, v[136:137]
	global_load_lds_dwordx4 v138, s[74:75]
	s_add_i32 m0, s29, 0x2000
	s_nop 0
	global_load_lds_dwordx4 v134, s[74:75]
	v_lshl_add_u64 v[248:249], s[72:73], 0, v[140:141]
	s_mov_b32 m0, s4
	s_nop 0
	global_load_lds_dwordx4 v[248:249], off
	s_mov_b32 m0, s5
	s_nop 0
	global_load_lds_dwordx4 v[170:171], off
	s_waitcnt vmcnt(8)
	s_waitcnt lgkmcnt(0)
	s_setprio 1
	v_mfma_f32_16x16x32_bf16 v[62:65], v[130:133], v[212:215], v[62:65]
	v_mfma_f32_16x16x32_bf16 v[54:57], v[184:187], v[212:215], v[54:57]
	v_mfma_f32_16x16x32_bf16 v[46:49], v[130:133], v[220:223], v[46:49]
	v_mfma_f32_16x16x32_bf16 v[38:41], v[184:187], v[220:223], v[38:41]
	v_mfma_f32_16x16x32_bf16 v[30:33], v[130:133], v[228:231], v[30:33]
	v_mfma_f32_16x16x32_bf16 v[22:25], v[184:187], v[228:231], v[22:25]
	v_mfma_f32_16x16x32_bf16 v[14:17], v[130:133], v[236:239], v[14:17]
	v_mfma_f32_16x16x32_bf16 v[6:9], v[184:187], v[236:239], v[6:9]
	v_mfma_f32_16x16x32_bf16 v[62:65], v[180:183], v[216:219], v[62:65]
	v_mfma_f32_16x16x32_bf16 v[54:57], v[188:191], v[216:219], v[54:57]
	v_mfma_f32_16x16x32_bf16 v[46:49], v[180:183], v[224:227], v[46:49]
	v_mfma_f32_16x16x32_bf16 v[38:41], v[188:191], v[224:227], v[38:41]
	v_mfma_f32_16x16x32_bf16 v[30:33], v[180:183], v[232:235], v[30:33]
	v_mfma_f32_16x16x32_bf16 v[22:25], v[188:191], v[232:235], v[22:25]
	v_mfma_f32_16x16x32_bf16 v[14:17], v[180:183], v[240:243], v[14:17]
	v_mfma_f32_16x16x32_bf16 v[6:9], v[188:191], v[240:243], v[6:9]
	v_mfma_f32_16x16x32_bf16 v[58:61], v[192:195], v[212:215], v[58:61]
	v_mfma_f32_16x16x32_bf16 v[50:53], v[204:207], v[212:215], v[50:53]
	v_mfma_f32_16x16x32_bf16 v[42:45], v[192:195], v[220:223], v[42:45]
	v_mfma_f32_16x16x32_bf16 v[34:37], v[204:207], v[220:223], v[34:37]
	v_mfma_f32_16x16x32_bf16 v[26:29], v[192:195], v[228:231], v[26:29]
	v_mfma_f32_16x16x32_bf16 v[18:21], v[204:207], v[228:231], v[18:21]
	v_mfma_f32_16x16x32_bf16 v[10:13], v[192:195], v[236:239], v[10:13]
	v_mfma_f32_16x16x32_bf16 v[2:5], v[204:207], v[236:239], v[2:5]
	v_mfma_f32_16x16x32_bf16 v[58:61], v[196:199], v[216:219], v[58:61]
	v_mfma_f32_16x16x32_bf16 v[50:53], v[208:211], v[216:219], v[50:53]
	v_mfma_f32_16x16x32_bf16 v[42:45], v[196:199], v[224:227], v[42:45]
	v_mfma_f32_16x16x32_bf16 v[34:37], v[208:211], v[224:227], v[34:37]
	v_mfma_f32_16x16x32_bf16 v[26:29], v[196:199], v[232:235], v[26:29]
	v_mfma_f32_16x16x32_bf16 v[18:21], v[208:211], v[232:235], v[18:21]
	v_mfma_f32_16x16x32_bf16 v[10:13], v[196:199], v[240:243], v[10:13]
	v_mfma_f32_16x16x32_bf16 v[2:5], v[208:211], v[240:243], v[2:5]
	s_barrier
	s_setprio 0
	s_add_i32 s29, 0, 0x18000
	v_add_u32_e32 v172, s29, v179
	s_add_i32 s37, 0, 0x1c000
	ds_read_b128 v[130:133], v172
	ds_read_b128 v[180:183], v172 offset:1024
	ds_read_b128 v[184:187], v172 offset:2048
	ds_read_b128 v[188:191], v172 offset:3072
	v_add_u32_e32 v172, s37, v179
	ds_read_b128 v[192:195], v172
	ds_read_b128 v[196:199], v172 offset:1024
	ds_read_b128 v[204:207], v172 offset:2048
	ds_read_b128 v[208:211], v172 offset:3072
	s_add_u32 s72, s72, 0x40000
	s_addc_u32 s73, s73, 0
	s_mov_b32 m0, s93
	ds_read_b128 v[212:215], v143 offset:32768
	ds_read_b128 v[216:219], v143 offset:33792
	ds_read_b128 v[220:223], v143 offset:34816
	ds_read_b128 v[224:227], v143 offset:35840
	ds_read_b128 v[228:231], v143 offset:36864
	ds_read_b128 v[232:235], v143 offset:37888
	ds_read_b128 v[236:239], v143 offset:38912
	ds_read_b128 v[240:243], v143 offset:39936
	global_load_lds_dwordx4 v140, s[72:73]
	s_mov_b32 m0, s33
	s_nop 0
	global_load_lds_dwordx4 v136, s[72:73]
	s_waitcnt vmcnt(8)
	s_waitcnt lgkmcnt(0)
	s_setprio 1
	v_mfma_f32_16x16x32_bf16 v[126:129], v[130:133], v[212:215], v[126:129]
	v_mfma_f32_16x16x32_bf16 v[118:121], v[184:187], v[212:215], v[118:121]
	v_mfma_f32_16x16x32_bf16 v[110:113], v[130:133], v[220:223], v[110:113]
	v_mfma_f32_16x16x32_bf16 v[102:105], v[184:187], v[220:223], v[102:105]
	v_mfma_f32_16x16x32_bf16 v[94:97], v[130:133], v[228:231], v[94:97]
	v_mfma_f32_16x16x32_bf16 v[86:89], v[184:187], v[228:231], v[86:89]
	v_mfma_f32_16x16x32_bf16 v[78:81], v[130:133], v[236:239], v[78:81]
	v_mfma_f32_16x16x32_bf16 v[70:73], v[184:187], v[236:239], v[70:73]
	v_mfma_f32_16x16x32_bf16 v[126:129], v[180:183], v[216:219], v[126:129]
	v_mfma_f32_16x16x32_bf16 v[118:121], v[188:191], v[216:219], v[118:121]
	v_mfma_f32_16x16x32_bf16 v[110:113], v[180:183], v[224:227], v[110:113]
	v_mfma_f32_16x16x32_bf16 v[102:105], v[188:191], v[224:227], v[102:105]
	v_mfma_f32_16x16x32_bf16 v[94:97], v[180:183], v[232:235], v[94:97]
	v_mfma_f32_16x16x32_bf16 v[86:89], v[188:191], v[232:235], v[86:89]
	v_mfma_f32_16x16x32_bf16 v[78:81], v[180:183], v[240:243], v[78:81]
	v_mfma_f32_16x16x32_bf16 v[70:73], v[188:191], v[240:243], v[70:73]
	v_mfma_f32_16x16x32_bf16 v[122:125], v[192:195], v[212:215], v[122:125]
	v_mfma_f32_16x16x32_bf16 v[114:117], v[204:207], v[212:215], v[114:117]
	v_mfma_f32_16x16x32_bf16 v[106:109], v[192:195], v[220:223], v[106:109]
	v_mfma_f32_16x16x32_bf16 v[98:101], v[204:207], v[220:223], v[98:101]
	v_mfma_f32_16x16x32_bf16 v[90:93], v[192:195], v[228:231], v[90:93]
	v_mfma_f32_16x16x32_bf16 v[82:85], v[204:207], v[228:231], v[82:85]
	v_mfma_f32_16x16x32_bf16 v[74:77], v[192:195], v[236:239], v[74:77]
	v_mfma_f32_16x16x32_bf16 v[66:69], v[204:207], v[236:239], v[66:69]
	v_mfma_f32_16x16x32_bf16 v[122:125], v[196:199], v[216:219], v[122:125]
	v_mfma_f32_16x16x32_bf16 v[114:117], v[208:211], v[216:219], v[114:117]
	v_mfma_f32_16x16x32_bf16 v[106:109], v[196:199], v[224:227], v[106:109]
	v_mfma_f32_16x16x32_bf16 v[98:101], v[208:211], v[224:227], v[98:101]
	v_mfma_f32_16x16x32_bf16 v[90:93], v[196:199], v[232:235], v[90:93]
	v_mfma_f32_16x16x32_bf16 v[82:85], v[208:211], v[232:235], v[82:85]
	v_mfma_f32_16x16x32_bf16 v[74:77], v[196:199], v[240:243], v[74:77]
	v_mfma_f32_16x16x32_bf16 v[66:69], v[208:211], v[240:243], v[66:69]
	s_barrier
	s_setprio 0
	s_add_i32 s29, s29, s84
	v_lshl_add_u64 v[172:173], v[244:245], 0, s[24:25]
	s_mov_b32 m0, s29
	ds_read_b128 v[212:215], v143 offset:49152
	ds_read_b128 v[216:219], v143 offset:50176
	ds_read_b128 v[220:223], v143 offset:51200
	ds_read_b128 v[224:227], v143 offset:52224
	ds_read_b128 v[228:231], v143 offset:53248
	ds_read_b128 v[232:235], v143 offset:54272
	ds_read_b128 v[236:239], v143 offset:55296
	ds_read_b128 v[240:243], v143 offset:56320
	global_load_lds_dwordx4 v[172:173], off
	s_add_i32 m0, s29, 0x2000
	s_add_u32 s42, s42, 0x40080
	v_lshl_add_u64 v[172:173], v[246:247], 0, s[24:25]
	s_addc_u32 s43, s43, 0
	s_add_i32 s29, s37, s84
	global_load_lds_dwordx4 v[172:173], off
	s_mov_b32 m0, s29
	v_lshl_add_u64 v[170:171], v[170:171], 0, s[24:25]
	global_load_lds_dwordx4 v138, s[42:43]
	s_add_i32 m0, s29, 0x2000
	s_nop 0
	global_load_lds_dwordx4 v134, s[42:43]
	v_lshl_add_u64 v[172:173], v[248:249], 0, s[24:25]
	s_mov_b32 m0, s97
	s_nop 0
	global_load_lds_dwordx4 v[172:173], off
	s_mov_b32 m0, s3
	s_nop 0
	global_load_lds_dwordx4 v[170:171], off
	s_waitcnt vmcnt(8)
	s_waitcnt lgkmcnt(0)
	s_setprio 1
	v_mfma_f32_16x16x32_bf16 v[62:65], v[130:133], v[212:215], v[62:65]
	v_mfma_f32_16x16x32_bf16 v[54:57], v[184:187], v[212:215], v[54:57]
	v_mfma_f32_16x16x32_bf16 v[46:49], v[130:133], v[220:223], v[46:49]
	v_mfma_f32_16x16x32_bf16 v[38:41], v[184:187], v[220:223], v[38:41]
	v_mfma_f32_16x16x32_bf16 v[30:33], v[130:133], v[228:231], v[30:33]
	v_mfma_f32_16x16x32_bf16 v[22:25], v[184:187], v[228:231], v[22:25]
	v_mfma_f32_16x16x32_bf16 v[14:17], v[130:133], v[236:239], v[14:17]
	v_mfma_f32_16x16x32_bf16 v[6:9], v[184:187], v[236:239], v[6:9]
	v_mfma_f32_16x16x32_bf16 v[62:65], v[180:183], v[216:219], v[62:65]
	v_mfma_f32_16x16x32_bf16 v[54:57], v[188:191], v[216:219], v[54:57]
	v_mfma_f32_16x16x32_bf16 v[46:49], v[180:183], v[224:227], v[46:49]
	v_mfma_f32_16x16x32_bf16 v[38:41], v[188:191], v[224:227], v[38:41]
	v_mfma_f32_16x16x32_bf16 v[30:33], v[180:183], v[232:235], v[30:33]
	v_mfma_f32_16x16x32_bf16 v[22:25], v[188:191], v[232:235], v[22:25]
	v_mfma_f32_16x16x32_bf16 v[14:17], v[180:183], v[240:243], v[14:17]
	v_mfma_f32_16x16x32_bf16 v[6:9], v[188:191], v[240:243], v[6:9]
	v_mfma_f32_16x16x32_bf16 v[58:61], v[192:195], v[212:215], v[58:61]
	v_mfma_f32_16x16x32_bf16 v[50:53], v[204:207], v[212:215], v[50:53]
	v_mfma_f32_16x16x32_bf16 v[42:45], v[192:195], v[220:223], v[42:45]
	v_mfma_f32_16x16x32_bf16 v[34:37], v[204:207], v[220:223], v[34:37]
	v_mfma_f32_16x16x32_bf16 v[26:29], v[192:195], v[228:231], v[26:29]
	v_mfma_f32_16x16x32_bf16 v[18:21], v[204:207], v[228:231], v[18:21]
	v_mfma_f32_16x16x32_bf16 v[10:13], v[192:195], v[236:239], v[10:13]
	v_mfma_f32_16x16x32_bf16 v[2:5], v[204:207], v[236:239], v[2:5]
	v_mfma_f32_16x16x32_bf16 v[58:61], v[196:199], v[216:219], v[58:61]
	v_mfma_f32_16x16x32_bf16 v[50:53], v[208:211], v[216:219], v[50:53]
	v_mfma_f32_16x16x32_bf16 v[42:45], v[196:199], v[224:227], v[42:45]
	v_mfma_f32_16x16x32_bf16 v[34:37], v[208:211], v[224:227], v[34:37]
	v_mfma_f32_16x16x32_bf16 v[26:29], v[196:199], v[232:235], v[26:29]
	v_mfma_f32_16x16x32_bf16 v[18:21], v[208:211], v[232:235], v[18:21]
	v_mfma_f32_16x16x32_bf16 v[10:13], v[196:199], v[240:243], v[10:13]
	v_mfma_f32_16x16x32_bf16 v[2:5], v[208:211], v[240:243], v[2:5]
	s_barrier
	s_setprio 0
	s_add_u32 s16, s16, 0x100
	s_addc_u32 s17, s17, 0
	s_add_u32 s56, s56, 0x100
	s_addc_u32 s57, s57, 0
	s_cmp_ge_i32 s86, s23
	s_mov_b32 s42, s86
	s_cbranch_scc0 .Lswi_loopL
.Lswi_exit:
	s_mov_b32 s56, s61

.LBB7_359:
.LBB7_360:
	v_and_b32_e32 v131, 64, v163
	v_xor_b32_e32 v130, 16, v163
	v_add_u32_e32 v131, 64, v131
	v_cmp_lt_i32_e32 vcc, v130, v131
	v_lshl_add_u32 v132, s38, 8, v142
	v_ashrrev_i32_e32 v133, 31, v132
	v_cndmask_b32_e32 v130, v163, v130, vcc
	v_lshlrev_b32_e32 v183, 2, v130
	v_xor_b32_e32 v130, 32, v163
	v_cmp_lt_i32_e32 vcc, v130, v131
	v_or_b32_e32 v172, 16, v132
	v_ashrrev_i32_e32 v173, 31, v172
	v_cndmask_b32_e32 v130, v163, v130, vcc
	v_lshlrev_b32_e32 v181, 2, v130
	v_lshlrev_b64 v[130:131], 6, v[132:133]
	v_lshl_add_u64 v[130:131], v[144:145], 0, v[130:131]
	v_lshlrev_b64 v[172:173], 6, v[172:173]
	v_lshl_add_u64 v[172:173], v[144:145], 0, v[172:173]
	s_lshl_b32 s9, s10, 7
	s_mov_b32 s10, 0x358637bd
	v_mov_b64_e32 v[190:191], s[10:11]
	s_movk_i32 s10, 0x2000
	s_or_b32 s9, s9, s96
	s_ashr_i32 s16, s9, 6
	s_ashr_i32 s17, s16, 31
	s_mul_i32 s13, s38, 0x160000
	s_lshl_b64 s[16:17], s[16:17], 15
	s_add_u32 s9, s70, s13
	s_waitcnt vmcnt(0)
	v_mov_b64_e32 v[184:185], v[204:205]
	v_mov_b64_e32 v[186:187], v[206:207]
	v_mov_b32_e32 v170, v185
	v_mov_b32_e32 v171, v186
	v_mov_b32_e32 v185, v187
	v_pk_add_f32 v[170:171], v[170:171], v[184:185]
	v_mov_b64_e32 v[184:185], v[208:209]
	v_mov_b64_e32 v[186:187], v[210:211]
	v_mov_b32_e32 v172, v185
	v_mov_b32_e32 v173, v186
	v_mov_b32_e32 v185, v187
	v_pk_add_f32 v[172:173], v[172:173], v[184:185]
	v_mov_b32_e32 v185, v170
	v_mov_b32_e32 v184, v172
	v_mov_b32_e32 v170, v173
	v_pk_add_f32 v[170:171], v[184:185], v[170:171]
	ds_bpermute_b32 v173, v183, v171
	ds_bpermute_b32 v172, v183, v170
	s_waitcnt lgkmcnt(0)
	v_pk_add_f32 v[170:171], v[170:171], v[172:173]
	ds_bpermute_b32 v173, v181, v171
	ds_bpermute_b32 v172, v181, v170
	s_waitcnt lgkmcnt(0)
	v_pk_add_f32 v[170:171], v[170:171], v[172:173]
	s_nop 0
	v_pk_fma_f32 v[170:171], v[170:171], s[26:27], v[190:191] op_sel_hi:[1,0,0]
	s_nop 0
	v_mul_f32_e32 v133, 0x4b800000, v171
	v_cmp_gt_f32_e64 s[42:43], s11, v171
	v_cmp_gt_f32_e32 vcc, s11, v170
	s_nop 0
	v_cndmask_b32_e64 v133, v171, v133, s[42:43]
	v_rsq_f32_e32 v133, v133
	s_nop 0
	v_mul_f32_e32 v171, 0x45800000, v133
	v_cndmask_b32_e64 v188, v133, v171, s[42:43]
	v_mul_f32_e32 v133, 0x4b800000, v170
	v_cndmask_b32_e32 v133, v170, v133, vcc
	v_rsq_f32_e32 v133, v133
	v_pk_mul_f32 v[126:127], v[126:127], v[188:189] op_sel_hi:[1,0]
	v_pk_mul_f32 v[122:123], v[122:123], v[188:189] op_sel_hi:[1,0]
	v_pk_mul_f32 v[124:125], v[124:125], v[188:189] op_sel_hi:[1,0]
	v_mul_f32_e32 v170, 0x45800000, v133
	v_cndmask_b32_e32 v186, v133, v170, vcc
	v_or_b32_e32 v170, 32, v132
	v_ashrrev_i32_e32 v171, 31, v170
	v_lshlrev_b64 v[170:171], 6, v[170:171]
	v_lshl_add_u64 v[170:171], v[144:145], 0, v[170:171]
	v_or_b32_e32 v132, 48, v132
	v_ashrrev_i32_e32 v133, 31, v132
	v_lshlrev_b64 v[132:133], 6, v[132:133]
	v_lshl_add_u64 v[132:133], v[144:145], 0, v[132:133]
	v_pk_mul_f32 v[122:123], v[126:127], v[122:123]
	v_pk_mul_f32 v[118:119], v[118:119], v[188:189] op_sel_hi:[1,0]
	v_pk_mul_f32 v[114:115], v[114:115], v[188:189] op_sel_hi:[1,0]
	v_pk_mul_f32 v[116:117], v[116:117], v[188:189] op_sel_hi:[1,0]
	v_pk_mul_f32 v[114:115], v[118:119], v[114:115]
	v_pk_mul_f32 v[110:111], v[110:111], v[186:187] op_sel_hi:[1,0]
	v_pk_mul_f32 v[106:107], v[106:107], v[186:187] op_sel_hi:[1,0]
	v_pk_mul_f32 v[108:109], v[108:109], v[186:187] op_sel_hi:[1,0]
	v_pk_mul_f32 v[106:107], v[110:111], v[106:107]
	v_pk_mul_f32 v[102:103], v[102:103], v[186:187] op_sel_hi:[1,0]
	v_pk_mul_f32 v[98:99], v[98:99], v[186:187] op_sel_hi:[1,0]
	v_pk_mul_f32 v[100:101], v[100:101], v[186:187] op_sel_hi:[1,0]
	v_pk_mul_f32 v[98:99], v[102:103], v[98:99]
	v_mov_b64_e32 v[192:193], v[212:213]
	v_mov_b64_e32 v[194:195], v[214:215]
	v_mov_b32_e32 v170, v193
	v_mov_b32_e32 v171, v194
	v_mov_b32_e32 v193, v195
	v_pk_add_f32 v[170:171], v[170:171], v[192:193]
	v_mov_b64_e32 v[192:193], v[216:217]
	v_mov_b64_e32 v[194:195], v[218:219]
	v_mov_b32_e32 v173, v170
	v_mov_b32_e32 v132, v193
	v_mov_b32_e32 v133, v194
	v_mov_b32_e32 v193, v195
	v_pk_add_f32 v[132:133], v[132:133], v[192:193]
	s_nop 0
	v_mov_b32_e32 v172, v132
	v_mov_b32_e32 v170, v133
	v_pk_add_f32 v[132:133], v[172:173], v[170:171]
	ds_bpermute_b32 v171, v183, v133
	ds_bpermute_b32 v170, v183, v132
	s_waitcnt lgkmcnt(0)
	v_pk_add_f32 v[132:133], v[132:133], v[170:171]
	ds_bpermute_b32 v171, v181, v133
	ds_bpermute_b32 v170, v181, v132
	s_waitcnt lgkmcnt(0)
	v_pk_add_f32 v[132:133], v[132:133], v[170:171]
	s_nop 0
	v_pk_fma_f32 v[132:133], v[132:133], s[26:27], v[190:191] op_sel_hi:[1,0,0]
	s_nop 0
	v_mul_f32_e32 v170, 0x4b800000, v133
	v_cmp_gt_f32_e64 s[42:43], s11, v133
	v_cmp_gt_f32_e32 vcc, s11, v132
	s_nop 0
	v_cndmask_b32_e64 v133, v133, v170, s[42:43]
	v_rsq_f32_e32 v133, v133
	s_nop 0
	v_mul_f32_e32 v170, 0x45800000, v133
	v_cndmask_b32_e64 v184, v133, v170, s[42:43]
	v_mul_f32_e32 v133, 0x4b800000, v132
	v_cndmask_b32_e32 v132, v132, v133, vcc
	v_rsq_f32_e32 v132, v132
	v_pk_mul_f32 v[94:95], v[94:95], v[184:185] op_sel_hi:[1,0]
	v_pk_mul_f32 v[90:91], v[90:91], v[184:185] op_sel_hi:[1,0]
	v_pk_mul_f32 v[92:93], v[92:93], v[184:185] op_sel_hi:[1,0]
	v_mul_f32_e32 v133, 0x45800000, v132
	v_cndmask_b32_e32 v182, v132, v133, vcc
	v_add_co_u32_e32 v170, vcc, s10, v130
	s_mul_hi_i32 s10, s38, 0x160000
	s_nop 0
	v_addc_co_u32_e32 v171, vcc, 0, v131, vcc
	s_addc_u32 s10, s71, s10
	s_add_u32 s16, s9, s16
	s_addc_u32 s17, s10, s17
	v_pk_mul_f32 v[90:91], v[94:95], v[90:91]
	v_pk_mul_f32 v[86:87], v[86:87], v[184:185] op_sel_hi:[1,0]
	v_pk_mul_f32 v[82:83], v[82:83], v[184:185] op_sel_hi:[1,0]
	v_pk_mul_f32 v[84:85], v[84:85], v[184:185] op_sel_hi:[1,0]
	v_pk_mul_f32 v[82:83], v[86:87], v[82:83]
	v_pk_mul_f32 v[78:79], v[78:79], v[182:183] op_sel_hi:[1,0]
	v_pk_mul_f32 v[74:75], v[74:75], v[182:183] op_sel_hi:[1,0]
	v_pk_mul_f32 v[76:77], v[76:77], v[182:183] op_sel_hi:[1,0]
	v_pk_mul_f32 v[74:75], v[78:79], v[74:75]
	v_pk_mul_f32 v[70:71], v[70:71], v[182:183] op_sel_hi:[1,0]
	v_pk_mul_f32 v[66:67], v[66:67], v[182:183] op_sel_hi:[1,0]
	v_pk_mul_f32 v[68:69], v[68:69], v[182:183] op_sel_hi:[1,0]
	v_pk_mul_f32 v[66:67], v[70:71], v[66:67]
	v_mov_b64_e32 v[130:131], v[220:221]
	v_mov_b64_e32 v[132:133], v[222:223]
	v_mov_b32_e32 v172, v131
	v_mov_b32_e32 v173, v132
	v_mov_b32_e32 v131, v133
	v_pk_add_f32 v[172:173], v[172:173], v[130:131]
	v_mov_b64_e32 v[130:131], v[224:225]
	v_mov_b64_e32 v[132:133], v[226:227]
	v_mov_b32_e32 v192, v131
	v_mov_b32_e32 v193, v132
	v_mov_b32_e32 v131, v133
	v_pk_add_f32 v[130:131], v[192:193], v[130:131]
	v_mov_b32_e32 v133, v172
	v_mov_b32_e32 v132, v130
	v_mov_b32_e32 v172, v131
	v_pk_add_f32 v[130:131], v[132:133], v[172:173]
	ds_bpermute_b32 v133, v183, v131
	ds_bpermute_b32 v132, v183, v130
	s_waitcnt lgkmcnt(0)
	v_pk_add_f32 v[130:131], v[130:131], v[132:133]
	ds_bpermute_b32 v133, v181, v131
	ds_bpermute_b32 v132, v181, v130
	s_waitcnt lgkmcnt(0)
	v_pk_add_f32 v[130:131], v[130:131], v[132:133]
	s_nop 0
	v_pk_fma_f32 v[130:131], v[130:131], s[26:27], v[190:191] op_sel_hi:[1,0,0]
	s_nop 0
	v_mul_f32_e32 v132, 0x4b800000, v131
	v_cmp_gt_f32_e64 s[42:43], s11, v131
	v_cmp_gt_f32_e32 vcc, s11, v130
	s_nop 0
	v_cndmask_b32_e64 v131, v131, v132, s[42:43]
	v_rsq_f32_e32 v131, v131
	s_nop 0
	v_mul_f32_e32 v132, 0x45800000, v131
	v_cndmask_b32_e64 v180, v131, v132, s[42:43]
	v_mul_f32_e32 v131, 0x4b800000, v130
	v_cndmask_b32_e32 v130, v130, v131, vcc
	v_rsq_f32_e32 v130, v130
	v_pk_mul_f32 v[62:63], v[62:63], v[180:181] op_sel_hi:[1,0]
	v_pk_mul_f32 v[58:59], v[58:59], v[180:181] op_sel_hi:[1,0]
	v_pk_mul_f32 v[60:61], v[60:61], v[180:181] op_sel_hi:[1,0]
	v_mul_f32_e32 v131, 0x45800000, v130
	v_cndmask_b32_e32 v178, v130, v131, vcc
	v_pk_mul_f32 v[58:59], v[62:63], v[58:59]
	v_pk_mul_f32 v[54:55], v[54:55], v[180:181] op_sel_hi:[1,0]
	v_pk_mul_f32 v[50:51], v[50:51], v[180:181] op_sel_hi:[1,0]
	v_pk_mul_f32 v[52:53], v[52:53], v[180:181] op_sel_hi:[1,0]
	v_pk_mul_f32 v[50:51], v[54:55], v[50:51]
	v_pk_mul_f32 v[46:47], v[46:47], v[178:179] op_sel_hi:[1,0]
	v_pk_mul_f32 v[42:43], v[42:43], v[178:179] op_sel_hi:[1,0]
	v_pk_mul_f32 v[44:45], v[44:45], v[178:179] op_sel_hi:[1,0]
	v_pk_mul_f32 v[42:43], v[46:47], v[42:43]
	v_pk_mul_f32 v[38:39], v[38:39], v[178:179] op_sel_hi:[1,0]
	v_pk_mul_f32 v[34:35], v[34:35], v[178:179] op_sel_hi:[1,0]
	v_pk_mul_f32 v[36:37], v[36:37], v[178:179] op_sel_hi:[1,0]
	v_pk_mul_f32 v[34:35], v[38:39], v[34:35]
	v_mov_b64_e32 v[130:131], v[228:229]
	v_mov_b64_e32 v[132:133], v[230:231]
	v_mov_b32_e32 v172, v131
	v_mov_b32_e32 v173, v132
	v_mov_b32_e32 v131, v133
	v_pk_add_f32 v[192:193], v[172:173], v[130:131]
	v_mov_b64_e32 v[130:131], v[232:233]
	v_mov_b64_e32 v[132:133], v[234:235]
	v_mov_b32_e32 v170, v131
	v_mov_b32_e32 v171, v132
	v_mov_b32_e32 v131, v133
	v_pk_add_f32 v[130:131], v[170:171], v[130:131]
	v_pk_mul_f32 v[170:171], v[126:127], s[30:31] op_sel_hi:[1,0]
	v_pk_mul_f32 v[126:127], v[128:129], v[188:189] op_sel_hi:[1,0]
	v_exp_f32_e32 v170, v170
	v_pk_mul_f32 v[128:129], v[126:127], s[30:31] op_sel_hi:[1,0]
	v_exp_f32_e32 v171, v171
	v_exp_f32_e32 v128, v128
	v_exp_f32_e32 v129, v129
	v_pk_mul_f32 v[124:125], v[126:127], v[124:125]
	v_pk_add_f32 v[170:171], v[170:171], 1.0 op_sel_hi:[1,0]
	v_mov_b32_e32 v132, v130
	v_pk_add_f32 v[128:129], v[128:129], 1.0 op_sel_hi:[1,0]
	v_rcp_f32_e32 v170, v170
	v_rcp_f32_e32 v171, v171
	v_rcp_f32_e32 v128, v128
	v_rcp_f32_e32 v129, v129
	v_mov_b32_e32 v133, v192
	v_pk_mul_f32 v[122:123], v[122:123], v[170:171]
	v_mov_b32_e32 v192, v131
	v_pk_mul_f32 v[124:125], v[124:125], v[128:129]
	v_cvt_pk_bf16_f32 v122, v122, v123
	v_pk_add_f32 v[130:131], v[132:133], v[192:193]
	v_cvt_pk_bf16_f32 v123, v124, v125
	v_pk_mul_f32 v[124:125], v[118:119], s[30:31] op_sel_hi:[1,0]
	ds_bpermute_b32 v133, v183, v131
	v_exp_f32_e32 v124, v124
	v_exp_f32_e32 v125, v125
	ds_bpermute_b32 v132, v183, v130
	v_pk_add_f32 v[124:125], v[124:125], 1.0 op_sel_hi:[1,0]
	s_nop 0
	v_rcp_f32_e32 v124, v124
	v_rcp_f32_e32 v125, v125
	s_waitcnt lgkmcnt(0)
	v_pk_add_f32 v[130:131], v[130:131], v[132:133]
	ds_bpermute_b32 v133, v181, v131
	ds_bpermute_b32 v132, v181, v130
	v_pk_mul_f32 v[114:115], v[114:115], v[124:125]
	s_waitcnt lgkmcnt(0)
	v_pk_add_f32 v[130:131], v[130:131], v[132:133]
	v_cvt_pk_bf16_f32 v124, v114, v115
	v_pk_mul_f32 v[114:115], v[120:121], v[188:189] op_sel_hi:[1,0]
	v_pk_fma_f32 v[130:131], v[130:131], s[26:27], v[190:191] op_sel_hi:[1,0,0]
	v_pk_mul_f32 v[118:119], v[114:115], s[30:31] op_sel_hi:[1,0]
	v_pk_mul_f32 v[114:115], v[114:115], v[116:117]
	v_exp_f32_e32 v118, v118
	v_exp_f32_e32 v119, v119
	v_mul_f32_e32 v132, 0x4b800000, v131
	v_cmp_gt_f32_e64 s[42:43], s11, v131
	v_cmp_gt_f32_e32 vcc, s11, v130
	v_pk_add_f32 v[118:119], v[118:119], 1.0 op_sel_hi:[1,0]
	v_cndmask_b32_e64 v131, v131, v132, s[42:43]
	v_rcp_f32_e32 v118, v118
	v_rcp_f32_e32 v119, v119
	v_rsq_f32_e32 v131, v131
	v_pk_mul_f32 v[114:115], v[114:115], v[118:119]
	s_nop 0
	v_cvt_pk_bf16_f32 v125, v114, v115
	v_lshl_add_u64 v[114:115], s[16:17], 0, v[146:147]
	v_lshl_add_u64 v[114:115], v[114:115], 0, v[0:1]
	global_store_dwordx4 v[114:115], v[122:125], off nt
	v_pk_mul_f32 v[114:115], v[110:111], s[30:31] op_sel_hi:[1,0]
	v_pk_mul_f32 v[110:111], v[112:113], v[186:187] op_sel_hi:[1,0]
	v_exp_f32_e32 v114, v114
	v_pk_mul_f32 v[112:113], v[110:111], s[30:31] op_sel_hi:[1,0]
	v_exp_f32_e32 v115, v115
	v_exp_f32_e32 v112, v112
	v_exp_f32_e32 v113, v113
	v_pk_mul_f32 v[108:109], v[110:111], v[108:109]
	v_pk_add_f32 v[114:115], v[114:115], 1.0 op_sel_hi:[1,0]
	v_pk_add_f32 v[112:113], v[112:113], 1.0 op_sel_hi:[1,0]
	v_rcp_f32_e32 v114, v114
	v_rcp_f32_e32 v115, v115
	v_rcp_f32_e32 v112, v112
	v_rcp_f32_e32 v113, v113
	v_mul_f32_e32 v132, 0x45800000, v131
	v_pk_mul_f32 v[106:107], v[106:107], v[114:115]
	v_cndmask_b32_e64 v132, v131, v132, s[42:43]
	v_pk_mul_f32 v[108:109], v[108:109], v[112:113]
	v_cvt_pk_bf16_f32 v106, v106, v107
	v_pk_mul_f32 v[30:31], v[30:31], v[132:133] op_sel_hi:[1,0]
	v_cvt_pk_bf16_f32 v107, v108, v109
	v_pk_mul_f32 v[108:109], v[102:103], s[30:31] op_sel_hi:[1,0]
	v_pk_mul_f32 v[26:27], v[26:27], v[132:133] op_sel_hi:[1,0]
	v_exp_f32_e32 v108, v108
	v_exp_f32_e32 v109, v109
	v_pk_mul_f32 v[26:27], v[30:31], v[26:27]
	v_pk_mul_f32 v[28:29], v[28:29], v[132:133] op_sel_hi:[1,0]
	v_pk_mul_f32 v[22:23], v[22:23], v[132:133] op_sel_hi:[1,0]
	v_pk_add_f32 v[108:109], v[108:109], 1.0 op_sel_hi:[1,0]
	v_pk_mul_f32 v[18:19], v[18:19], v[132:133] op_sel_hi:[1,0]
	v_rcp_f32_e32 v108, v108
	v_rcp_f32_e32 v109, v109
	v_pk_mul_f32 v[18:19], v[22:23], v[18:19]
	v_mul_f32_e32 v131, 0x4b800000, v130
	v_cndmask_b32_e32 v130, v130, v131, vcc
	v_pk_mul_f32 v[98:99], v[98:99], v[108:109]
	v_rsq_f32_e32 v130, v130
	v_cvt_pk_bf16_f32 v108, v98, v99
	v_pk_mul_f32 v[98:99], v[104:105], v[186:187] op_sel_hi:[1,0]
	v_pk_mul_f32 v[20:21], v[20:21], v[132:133] op_sel_hi:[1,0]
	v_pk_mul_f32 v[102:103], v[98:99], s[30:31] op_sel_hi:[1,0]
	v_pk_mul_f32 v[98:99], v[98:99], v[100:101]
	v_exp_f32_e32 v102, v102
	v_exp_f32_e32 v103, v103
	v_mul_f32_e32 v131, 0x45800000, v130
	v_cndmask_b32_e32 v130, v130, v131, vcc
	v_pk_mul_f32 v[14:15], v[14:15], v[130:131] op_sel_hi:[1,0]
	v_pk_add_f32 v[102:103], v[102:103], 1.0 op_sel_hi:[1,0]
	v_pk_mul_f32 v[10:11], v[10:11], v[130:131] op_sel_hi:[1,0]
	v_rcp_f32_e32 v102, v102
	v_rcp_f32_e32 v103, v103
	v_pk_mul_f32 v[10:11], v[14:15], v[10:11]
	v_pk_mul_f32 v[12:13], v[12:13], v[130:131] op_sel_hi:[1,0]
	v_pk_mul_f32 v[6:7], v[6:7], v[130:131] op_sel_hi:[1,0]
	v_pk_mul_f32 v[98:99], v[98:99], v[102:103]
	v_pk_mul_f32 v[2:3], v[2:3], v[130:131] op_sel_hi:[1,0]
	v_cvt_pk_bf16_f32 v109, v98, v99
	v_lshl_add_u64 v[98:99], s[16:17], 0, v[148:149]
	v_lshl_add_u64 v[98:99], v[98:99], 0, v[0:1]
	global_store_dwordx4 v[98:99], v[106:109], off nt
	v_pk_mul_f32 v[98:99], v[94:95], s[30:31] op_sel_hi:[1,0]
	v_pk_mul_f32 v[94:95], v[96:97], v[184:185] op_sel_hi:[1,0]
	v_exp_f32_e32 v98, v98
	v_pk_mul_f32 v[96:97], v[94:95], s[30:31] op_sel_hi:[1,0]
	v_exp_f32_e32 v99, v99
	v_exp_f32_e32 v96, v96
	v_exp_f32_e32 v97, v97
	v_pk_mul_f32 v[92:93], v[94:95], v[92:93]
	v_pk_add_f32 v[98:99], v[98:99], 1.0 op_sel_hi:[1,0]
	v_pk_add_f32 v[96:97], v[96:97], 1.0 op_sel_hi:[1,0]
	v_rcp_f32_e32 v98, v98
	v_rcp_f32_e32 v99, v99
	v_rcp_f32_e32 v96, v96
	v_rcp_f32_e32 v97, v97
	v_pk_mul_f32 v[2:3], v[6:7], v[2:3]
	v_pk_mul_f32 v[90:91], v[90:91], v[98:99]
	v_pk_mul_f32 v[4:5], v[4:5], v[130:131] op_sel_hi:[1,0]
	v_pk_mul_f32 v[92:93], v[92:93], v[96:97]
	v_cvt_pk_bf16_f32 v90, v90, v91
	s_andn2_b64 vcc, exec, s[40:41]
	v_cvt_pk_bf16_f32 v91, v92, v93
	v_pk_mul_f32 v[92:93], v[86:87], s[30:31] op_sel_hi:[1,0]
	s_nop 0
	v_exp_f32_e32 v92, v92
	v_exp_f32_e32 v93, v93
	s_nop 0
	v_pk_add_f32 v[92:93], v[92:93], 1.0 op_sel_hi:[1,0]
	s_nop 0
	v_rcp_f32_e32 v92, v92
	v_rcp_f32_e32 v93, v93
	s_nop 0
	v_pk_mul_f32 v[82:83], v[82:83], v[92:93]
	s_nop 0
	v_cvt_pk_bf16_f32 v92, v82, v83
	v_pk_mul_f32 v[82:83], v[88:89], v[184:185] op_sel_hi:[1,0]
	s_nop 0
	v_pk_mul_f32 v[86:87], v[82:83], s[30:31] op_sel_hi:[1,0]
	v_pk_mul_f32 v[82:83], v[82:83], v[84:85]
	v_exp_f32_e32 v86, v86
	v_exp_f32_e32 v87, v87
	s_nop 0
	v_pk_add_f32 v[86:87], v[86:87], 1.0 op_sel_hi:[1,0]
	s_nop 0
	v_rcp_f32_e32 v86, v86
	v_rcp_f32_e32 v87, v87
	s_nop 0
	v_pk_mul_f32 v[82:83], v[82:83], v[86:87]
	s_nop 0
	v_cvt_pk_bf16_f32 v93, v82, v83
	v_lshl_add_u64 v[82:83], s[16:17], 0, v[150:151]
	v_lshl_add_u64 v[82:83], v[82:83], 0, v[0:1]
	global_store_dwordx4 v[82:83], v[90:93], off nt
	v_pk_mul_f32 v[82:83], v[78:79], s[30:31] op_sel_hi:[1,0]
	v_pk_mul_f32 v[78:79], v[80:81], v[182:183] op_sel_hi:[1,0]
	v_exp_f32_e32 v82, v82
	v_pk_mul_f32 v[80:81], v[78:79], s[30:31] op_sel_hi:[1,0]
	v_exp_f32_e32 v83, v83
	v_exp_f32_e32 v80, v80
	v_exp_f32_e32 v81, v81
	v_pk_mul_f32 v[76:77], v[78:79], v[76:77]
	v_pk_add_f32 v[82:83], v[82:83], 1.0 op_sel_hi:[1,0]
	v_pk_add_f32 v[80:81], v[80:81], 1.0 op_sel_hi:[1,0]
	v_rcp_f32_e32 v82, v82
	v_rcp_f32_e32 v83, v83
	v_rcp_f32_e32 v80, v80
	v_rcp_f32_e32 v81, v81
	v_pk_mul_f32 v[74:75], v[74:75], v[82:83]
	s_nop 0
	v_cvt_pk_bf16_f32 v74, v74, v75
	v_pk_mul_f32 v[76:77], v[76:77], v[80:81]
	s_nop 0
	v_cvt_pk_bf16_f32 v75, v76, v77
	v_pk_mul_f32 v[76:77], v[70:71], s[30:31] op_sel_hi:[1,0]
	s_nop 0
	v_exp_f32_e32 v76, v76
	v_exp_f32_e32 v77, v77
	s_nop 0
	v_pk_add_f32 v[76:77], v[76:77], 1.0 op_sel_hi:[1,0]
	s_nop 0
	v_rcp_f32_e32 v76, v76
	v_rcp_f32_e32 v77, v77
	s_nop 0
	v_pk_mul_f32 v[66:67], v[66:67], v[76:77]
	s_nop 0
	v_cvt_pk_bf16_f32 v76, v66, v67
	v_pk_mul_f32 v[66:67], v[72:73], v[182:183] op_sel_hi:[1,0]
	s_nop 0
	v_pk_mul_f32 v[70:71], v[66:67], s[30:31] op_sel_hi:[1,0]
	v_pk_mul_f32 v[66:67], v[66:67], v[68:69]
	v_exp_f32_e32 v70, v70
	v_exp_f32_e32 v71, v71
	s_nop 0
	v_pk_add_f32 v[70:71], v[70:71], 1.0 op_sel_hi:[1,0]
	s_nop 0
	v_rcp_f32_e32 v70, v70
	v_rcp_f32_e32 v71, v71
	s_nop 0
	v_pk_mul_f32 v[66:67], v[66:67], v[70:71]
	s_nop 0
	v_cvt_pk_bf16_f32 v77, v66, v67
	v_lshl_add_u64 v[66:67], s[16:17], 0, v[152:153]
	v_lshl_add_u64 v[66:67], v[66:67], 0, v[0:1]
	global_store_dwordx4 v[66:67], v[74:77], off nt
	v_pk_mul_f32 v[66:67], v[62:63], s[30:31] op_sel_hi:[1,0]
	v_pk_mul_f32 v[62:63], v[64:65], v[180:181] op_sel_hi:[1,0]
	v_exp_f32_e32 v66, v66
	v_pk_mul_f32 v[64:65], v[62:63], s[30:31] op_sel_hi:[1,0]
	v_exp_f32_e32 v67, v67
	v_exp_f32_e32 v64, v64
	v_exp_f32_e32 v65, v65
	v_pk_mul_f32 v[60:61], v[62:63], v[60:61]
	v_pk_add_f32 v[66:67], v[66:67], 1.0 op_sel_hi:[1,0]
	v_pk_add_f32 v[64:65], v[64:65], 1.0 op_sel_hi:[1,0]
	v_rcp_f32_e32 v66, v66
	v_rcp_f32_e32 v67, v67
	v_rcp_f32_e32 v64, v64
	v_rcp_f32_e32 v65, v65
	v_pk_mul_f32 v[58:59], v[58:59], v[66:67]
	s_nop 0
	v_cvt_pk_bf16_f32 v58, v58, v59
	v_pk_mul_f32 v[60:61], v[60:61], v[64:65]
	s_nop 0
	v_cvt_pk_bf16_f32 v59, v60, v61
	v_pk_mul_f32 v[60:61], v[54:55], s[30:31] op_sel_hi:[1,0]
	s_nop 0
	v_exp_f32_e32 v60, v60
	v_exp_f32_e32 v61, v61
	s_nop 0
	v_pk_add_f32 v[60:61], v[60:61], 1.0 op_sel_hi:[1,0]
	s_nop 0
	v_rcp_f32_e32 v60, v60
	v_rcp_f32_e32 v61, v61
	s_nop 0
	v_pk_mul_f32 v[50:51], v[50:51], v[60:61]
	s_nop 0
	v_cvt_pk_bf16_f32 v60, v50, v51
	v_pk_mul_f32 v[50:51], v[56:57], v[180:181] op_sel_hi:[1,0]
	s_nop 0
	v_pk_mul_f32 v[54:55], v[50:51], s[30:31] op_sel_hi:[1,0]
	v_pk_mul_f32 v[50:51], v[50:51], v[52:53]
	v_exp_f32_e32 v54, v54
	v_exp_f32_e32 v55, v55
	s_nop 0
	v_pk_add_f32 v[54:55], v[54:55], 1.0 op_sel_hi:[1,0]
	s_nop 0
	v_rcp_f32_e32 v54, v54
	v_rcp_f32_e32 v55, v55
	s_nop 0
	v_pk_mul_f32 v[50:51], v[50:51], v[54:55]
	s_nop 0
	v_cvt_pk_bf16_f32 v61, v50, v51
	v_lshl_add_u64 v[50:51], s[16:17], 0, v[154:155]
	v_lshl_add_u64 v[50:51], v[50:51], 0, v[0:1]
	global_store_dwordx4 v[50:51], v[58:61], off nt
	v_pk_mul_f32 v[50:51], v[46:47], s[30:31] op_sel_hi:[1,0]
	v_pk_mul_f32 v[46:47], v[48:49], v[178:179] op_sel_hi:[1,0]
	v_exp_f32_e32 v50, v50
	v_pk_mul_f32 v[48:49], v[46:47], s[30:31] op_sel_hi:[1,0]
	v_exp_f32_e32 v51, v51
	v_exp_f32_e32 v48, v48
	v_exp_f32_e32 v49, v49
	v_pk_mul_f32 v[44:45], v[46:47], v[44:45]
	v_pk_add_f32 v[50:51], v[50:51], 1.0 op_sel_hi:[1,0]
	v_pk_add_f32 v[48:49], v[48:49], 1.0 op_sel_hi:[1,0]
	v_rcp_f32_e32 v50, v50
	v_rcp_f32_e32 v51, v51
	v_rcp_f32_e32 v48, v48
	v_rcp_f32_e32 v49, v49
	v_pk_mul_f32 v[42:43], v[42:43], v[50:51]
	s_nop 0
	v_cvt_pk_bf16_f32 v42, v42, v43
	v_pk_mul_f32 v[44:45], v[44:45], v[48:49]
	s_nop 0
	v_cvt_pk_bf16_f32 v43, v44, v45
	v_pk_mul_f32 v[44:45], v[38:39], s[30:31] op_sel_hi:[1,0]
	s_nop 0
	v_exp_f32_e32 v44, v44
	v_exp_f32_e32 v45, v45
	s_nop 0
	v_pk_add_f32 v[44:45], v[44:45], 1.0 op_sel_hi:[1,0]
	s_nop 0
	v_rcp_f32_e32 v44, v44
	v_rcp_f32_e32 v45, v45
	s_nop 0
	v_pk_mul_f32 v[34:35], v[34:35], v[44:45]
	s_nop 0
	v_cvt_pk_bf16_f32 v44, v34, v35
	v_pk_mul_f32 v[34:35], v[40:41], v[178:179] op_sel_hi:[1,0]
	s_nop 0
	v_pk_mul_f32 v[38:39], v[34:35], s[30:31] op_sel_hi:[1,0]
	v_pk_mul_f32 v[34:35], v[34:35], v[36:37]
	v_exp_f32_e32 v38, v38
	v_exp_f32_e32 v39, v39
	s_nop 0
	v_pk_add_f32 v[38:39], v[38:39], 1.0 op_sel_hi:[1,0]
	s_nop 0
	v_rcp_f32_e32 v38, v38
	v_rcp_f32_e32 v39, v39
	s_nop 0
	v_pk_mul_f32 v[34:35], v[34:35], v[38:39]
	s_nop 0
	v_cvt_pk_bf16_f32 v45, v34, v35
	v_lshl_add_u64 v[34:35], s[16:17], 0, v[156:157]
	v_lshl_add_u64 v[34:35], v[34:35], 0, v[0:1]
	global_store_dwordx4 v[34:35], v[42:45], off nt
	v_pk_mul_f32 v[34:35], v[30:31], s[30:31] op_sel_hi:[1,0]
	v_pk_mul_f32 v[30:31], v[32:33], v[132:133] op_sel_hi:[1,0]
	v_exp_f32_e32 v34, v34
	v_pk_mul_f32 v[32:33], v[30:31], s[30:31] op_sel_hi:[1,0]
	v_exp_f32_e32 v35, v35
	v_exp_f32_e32 v32, v32
	v_exp_f32_e32 v33, v33
	v_pk_mul_f32 v[28:29], v[30:31], v[28:29]
	v_pk_add_f32 v[34:35], v[34:35], 1.0 op_sel_hi:[1,0]
	v_pk_add_f32 v[32:33], v[32:33], 1.0 op_sel_hi:[1,0]
	v_rcp_f32_e32 v34, v34
	v_rcp_f32_e32 v35, v35
	v_rcp_f32_e32 v32, v32
	v_rcp_f32_e32 v33, v33
	v_pk_mul_f32 v[26:27], v[26:27], v[34:35]
	s_nop 0
	v_cvt_pk_bf16_f32 v26, v26, v27
	v_pk_mul_f32 v[28:29], v[28:29], v[32:33]
	s_nop 0
	v_cvt_pk_bf16_f32 v27, v28, v29
	v_pk_mul_f32 v[28:29], v[22:23], s[30:31] op_sel_hi:[1,0]
	s_nop 0
	v_exp_f32_e32 v28, v28
	v_exp_f32_e32 v29, v29
	s_nop 0
	v_pk_add_f32 v[28:29], v[28:29], 1.0 op_sel_hi:[1,0]
	s_nop 0
	v_rcp_f32_e32 v28, v28
	v_rcp_f32_e32 v29, v29
	s_nop 0
	v_pk_mul_f32 v[18:19], v[18:19], v[28:29]
	s_nop 0
	v_cvt_pk_bf16_f32 v28, v18, v19
	v_pk_mul_f32 v[18:19], v[24:25], v[132:133] op_sel_hi:[1,0]
	s_nop 0
	v_pk_mul_f32 v[22:23], v[18:19], s[30:31] op_sel_hi:[1,0]
	v_pk_mul_f32 v[18:19], v[18:19], v[20:21]
	v_exp_f32_e32 v22, v22
	v_exp_f32_e32 v23, v23
	s_nop 0
	v_pk_add_f32 v[22:23], v[22:23], 1.0 op_sel_hi:[1,0]
	s_nop 0
	v_rcp_f32_e32 v22, v22
	v_rcp_f32_e32 v23, v23
	s_nop 0
	v_pk_mul_f32 v[18:19], v[18:19], v[22:23]
	s_nop 0
	v_cvt_pk_bf16_f32 v29, v18, v19
	v_lshl_add_u64 v[18:19], s[16:17], 0, v[158:159]
	v_lshl_add_u64 v[18:19], v[18:19], 0, v[0:1]
	global_store_dwordx4 v[18:19], v[26:29], off nt
	v_pk_mul_f32 v[18:19], v[14:15], s[30:31] op_sel_hi:[1,0]
	v_pk_mul_f32 v[14:15], v[16:17], v[130:131] op_sel_hi:[1,0]
	v_exp_f32_e32 v18, v18
	v_pk_mul_f32 v[16:17], v[14:15], s[30:31] op_sel_hi:[1,0]
	v_exp_f32_e32 v19, v19
	v_exp_f32_e32 v16, v16
	v_exp_f32_e32 v17, v17
	v_pk_mul_f32 v[12:13], v[14:15], v[12:13]
	v_pk_add_f32 v[18:19], v[18:19], 1.0 op_sel_hi:[1,0]
	v_pk_add_f32 v[16:17], v[16:17], 1.0 op_sel_hi:[1,0]
	v_rcp_f32_e32 v18, v18
	v_rcp_f32_e32 v19, v19
	v_rcp_f32_e32 v16, v16
	v_rcp_f32_e32 v17, v17
	v_pk_mul_f32 v[10:11], v[10:11], v[18:19]
	s_nop 0
	v_cvt_pk_bf16_f32 v10, v10, v11
	v_pk_mul_f32 v[12:13], v[12:13], v[16:17]
	s_nop 0
	v_cvt_pk_bf16_f32 v11, v12, v13
	v_pk_mul_f32 v[12:13], v[6:7], s[30:31] op_sel_hi:[1,0]
	s_nop 0
	v_exp_f32_e32 v12, v12
	v_exp_f32_e32 v13, v13
	s_nop 0
	v_pk_add_f32 v[12:13], v[12:13], 1.0 op_sel_hi:[1,0]
	s_nop 0
	v_rcp_f32_e32 v12, v12
	v_rcp_f32_e32 v13, v13
	s_nop 0
	v_pk_mul_f32 v[2:3], v[2:3], v[12:13]
	s_nop 0
	v_cvt_pk_bf16_f32 v12, v2, v3
	v_pk_mul_f32 v[2:3], v[8:9], v[130:131] op_sel_hi:[1,0]
	s_nop 0
	v_pk_mul_f32 v[6:7], v[2:3], s[30:31] op_sel_hi:[1,0]
	v_pk_mul_f32 v[2:3], v[2:3], v[4:5]
	v_exp_f32_e32 v6, v6
	v_exp_f32_e32 v7, v7
	s_nop 0
	v_pk_add_f32 v[6:7], v[6:7], 1.0 op_sel_hi:[1,0]
	s_nop 0
	v_rcp_f32_e32 v6, v6
	v_rcp_f32_e32 v7, v7
	s_nop 0
	v_pk_mul_f32 v[2:3], v[2:3], v[6:7]
	s_nop 0
	v_cvt_pk_bf16_f32 v13, v2, v3
	v_lshl_add_u64 v[2:3], s[16:17], 0, v[160:161]
	v_lshl_add_u64 v[2:3], v[2:3], 0, v[0:1]
	global_store_dwordx4 v[2:3], v[10:13], off nt
	s_mov_b64 s[16:17], -1
	s_cbranch_vccnz .LBB7_352
	s_andn2_b64 vcc, exec, s[50:51]
	s_cbranch_vccnz .LBB7_351
	s_branch .LBB7_351
